# v47 + trailing s_setprio 0 moved behind the phase-end barrier in the six k-loops (shorter MFMA-to-barrier path)
# speedup vs baseline: 1.0056x; 1.0056x over previous
; #define PG8_STAGE(bufoff, gbase, voff) do { _Pragma("unroll") for (int _i = 0; _i < 2; ++_i) \
;         __builtin_amdgcn_global_load_lds((const unsigned*)((const char*)(gbase) + (voff)[_i]), (LAS unsigned*)(lds + (bufoff) + ldsw + _i * 8192), 16, 0, 0); } while (0)
; #define PG8_LDA(dst, b, h) do { _Pragma("unroll") for (int m = 0; m < 4; ++m) _Pragma("unroll") for (int k = 0; k < 2; ++k) dst[m][k] = *(const LAS bf16x8*)(lds + PG8_SA(b, h) + aoff + m * 2048 + k * 1024); } while (0)
; #define PG8_MMA(ai, bj, At, Bt) do { __builtin_amdgcn_s_setprio(1); _Pragma("unroll") for (int m = 0; m < 4; ++m) _Pragma("unroll") for (int n = 0; n < 2; ++n) _Pragma("unroll") for (int k = 0; k < 2; ++k) \
;         acc[ai][bj][m][n] = __builtin_amdgcn_mfma_f32_16x16x32_bf16(Bt[n][k], At[m][k], acc[ai][bj][m][n], 0, 0, 0); __builtin_amdgcn_s_setprio(0); } while (0)
; #define PG8_WAIT_V(n) asm volatile("s_waitcnt vmcnt(" #n ")" ::: "memory")
; #define PG8_WAIT_L(n) asm volatile("s_waitcnt lgkmcnt(" #n ")" ::: "memory")
; #define PG8_BAR __builtin_amdgcn_s_barrier()
; #define PG8_SCHED __builtin_amdgcn_sched_barrier(0)
; template <class Epi, class Sched, int NSEG, int KK, int LDA, int LDB>
; __device__ __forceinline__ void gemm_phase(LAS unsigned char* lds, const Gemm g, const Sched& S, const Epi& E) {
;     ...
;             PG8_WAIT_V(8); PG8_WAIT_L(0); PG8_BAR; PG8_MMA(0, 0, At, B0); PG8_MMA(0, 1, At, B1); PG8_BAR; PG8_SCHED;
;             PG8_LDA(At, 0, 1); PG8_STAGE(PG8_SB(0, 0), b2, voffB); PG8_STAGE(PG8_SB(0, 1), b2 + hstepB, voffB); PG8_STAGE(PG8_SA(0, 0), a2, voffA);
;             PG8_WAIT_V(8); PG8_WAIT_L(0); PG8_BAR; PG8_MMA(1, 0, At, B0); PG8_MMA(1, 1, At, B1); PG8_BAR; PG8_SCHED;
.Lskw_0_1:
	s_waitcnt lgkmcnt(0)
	s_barrier
	s_setprio 1
	v_mfma_f32_16x16x32_bf16 v[126:129], v[130:133], v[188:191], v[126:129]
	v_mfma_f32_16x16x32_bf16 v[122:125], v[138:141], v[188:191], v[122:125]
	v_mfma_f32_16x16x32_bf16 v[110:113], v[130:133], v[196:199], v[110:113]
	v_mfma_f32_16x16x32_bf16 v[106:109], v[138:141], v[196:199], v[106:109]
	v_mfma_f32_16x16x32_bf16 v[94:97], v[130:133], v[204:207], v[94:97]
	v_mfma_f32_16x16x32_bf16 v[90:93], v[138:141], v[204:207], v[90:93]
	v_mfma_f32_16x16x32_bf16 v[78:81], v[130:133], v[212:215], v[78:81]
	v_mfma_f32_16x16x32_bf16 v[74:77], v[138:141], v[212:215], v[74:77]
	v_mfma_f32_16x16x32_bf16 v[126:129], v[134:137], v[192:195], v[126:129]
	v_mfma_f32_16x16x32_bf16 v[122:125], v[158:161], v[192:195], v[122:125]
	v_mfma_f32_16x16x32_bf16 v[110:113], v[134:137], v[200:203], v[110:113]
	v_mfma_f32_16x16x32_bf16 v[106:109], v[158:161], v[200:203], v[106:109]
	v_mfma_f32_16x16x32_bf16 v[94:97], v[134:137], v[208:211], v[94:97]
	v_mfma_f32_16x16x32_bf16 v[90:93], v[158:161], v[208:211], v[90:93]
	v_mfma_f32_16x16x32_bf16 v[78:81], v[134:137], v[216:219], v[78:81]
	v_mfma_f32_16x16x32_bf16 v[74:77], v[158:161], v[216:219], v[74:77]
	s_setprio 0
	s_setprio 1
	v_mfma_f32_16x16x32_bf16 v[118:121], v[162:165], v[188:191], v[118:121]
	v_mfma_f32_16x16x32_bf16 v[114:117], v[180:183], v[188:191], v[114:117]
	v_mfma_f32_16x16x32_bf16 v[102:105], v[162:165], v[196:199], v[102:105]
	v_mfma_f32_16x16x32_bf16 v[98:101], v[180:183], v[196:199], v[98:101]
	v_mfma_f32_16x16x32_bf16 v[86:89], v[162:165], v[204:207], v[86:89]
	v_mfma_f32_16x16x32_bf16 v[82:85], v[180:183], v[204:207], v[82:85]
	v_mfma_f32_16x16x32_bf16 v[70:73], v[162:165], v[212:215], v[70:73]
	v_mfma_f32_16x16x32_bf16 v[66:69], v[180:183], v[212:215], v[66:69]
	v_mfma_f32_16x16x32_bf16 v[118:121], v[176:179], v[192:195], v[118:121]
	v_mfma_f32_16x16x32_bf16 v[114:117], v[184:187], v[192:195], v[114:117]
	v_mfma_f32_16x16x32_bf16 v[102:105], v[176:179], v[200:203], v[102:105]
	v_mfma_f32_16x16x32_bf16 v[98:101], v[184:187], v[200:203], v[98:101]
	v_mfma_f32_16x16x32_bf16 v[86:89], v[176:179], v[208:211], v[86:89]
	v_mfma_f32_16x16x32_bf16 v[82:85], v[184:187], v[208:211], v[82:85]
	v_mfma_f32_16x16x32_bf16 v[70:73], v[176:179], v[216:219], v[70:73]
	v_mfma_f32_16x16x32_bf16 v[66:69], v[184:187], v[216:219], v[66:69]
	s_barrier
	s_setprio 0
	s_add_i32 s63, s63, s13
	v_lshl_add_u64 v[154:155], s[10:11], 0, v[146:147]
	s_mov_b32 m0, s63
	ds_read_b128 v[188:191], v157 offset:16384
	ds_read_b128 v[192:195], v157 offset:17408
	ds_read_b128 v[196:199], v157 offset:18432
	ds_read_b128 v[200:203], v157 offset:19456
	ds_read_b128 v[204:207], v157 offset:20480
	ds_read_b128 v[208:211], v157 offset:21504
	ds_read_b128 v[212:215], v157 offset:22528
	ds_read_b128 v[216:219], v157 offset:23552
	global_load_lds_dwordx4 v[154:155], off
	s_add_i32 m0, s63, 0x2000
	s_add_u32 s94, s10, 0x40000
	v_lshl_add_u64 v[166:167], s[10:11], 0, v[142:143]
	s_addc_u32 s95, s11, 0
	s_add_i32 s63, s77, s13
	global_load_lds_dwordx4 v[166:167], off
	v_lshl_add_u64 v[220:221], s[94:95], 0, v[146:147]
	s_mov_b32 m0, s63
	v_lshl_add_u64 v[222:223], s[50:51], 0, v[144:145]
	global_load_lds_dwordx4 v[220:221], off
	v_lshl_add_u64 v[220:221], s[94:95], 0, v[142:143]
	s_add_i32 m0, s63, 0x2000
	s_nop 0
	global_load_lds_dwordx4 v[220:221], off
	v_lshl_add_u64 v[220:221], s[50:51], 0, v[148:149]
	s_mov_b32 m0, s22
	s_nop 0
	global_load_lds_dwordx4 v[220:221], off
	s_mov_b32 m0, s23
	s_nop 0
	global_load_lds_dwordx4 v[222:223], off
	s_cmp_lg_u32 s101, 0
	s_cbranch_scc1 .Lskw_0_2
	s_waitcnt vmcnt(8)
.Lskw_0_2:
	s_mov_b32 s101, 0
	s_waitcnt lgkmcnt(0)
	s_barrier
	s_setprio 1
	v_mfma_f32_16x16x32_bf16 v[62:65], v[130:133], v[188:191], v[62:65]
	v_mfma_f32_16x16x32_bf16 v[58:61], v[138:141], v[188:191], v[58:61]
	v_mfma_f32_16x16x32_bf16 v[46:49], v[130:133], v[196:199], v[46:49]
	v_mfma_f32_16x16x32_bf16 v[42:45], v[138:141], v[196:199], v[42:45]
	v_mfma_f32_16x16x32_bf16 v[30:33], v[130:133], v[204:207], v[30:33]
	v_mfma_f32_16x16x32_bf16 v[26:29], v[138:141], v[204:207], v[26:29]
	v_mfma_f32_16x16x32_bf16 v[14:17], v[130:133], v[212:215], v[14:17]
	v_mfma_f32_16x16x32_bf16 v[10:13], v[138:141], v[212:215], v[10:13]
	v_mfma_f32_16x16x32_bf16 v[62:65], v[134:137], v[192:195], v[62:65]
	v_mfma_f32_16x16x32_bf16 v[58:61], v[158:161], v[192:195], v[58:61]
	v_mfma_f32_16x16x32_bf16 v[46:49], v[134:137], v[200:203], v[46:49]
	v_mfma_f32_16x16x32_bf16 v[42:45], v[158:161], v[200:203], v[42:45]
	v_mfma_f32_16x16x32_bf16 v[30:33], v[134:137], v[208:211], v[30:33]
	v_mfma_f32_16x16x32_bf16 v[26:29], v[158:161], v[208:211], v[26:29]
	v_mfma_f32_16x16x32_bf16 v[14:17], v[134:137], v[216:219], v[14:17]
	v_mfma_f32_16x16x32_bf16 v[10:13], v[158:161], v[216:219], v[10:13]
	s_setprio 0
	s_setprio 1
	v_mfma_f32_16x16x32_bf16 v[54:57], v[162:165], v[188:191], v[54:57]
	v_mfma_f32_16x16x32_bf16 v[50:53], v[180:183], v[188:191], v[50:53]
	v_mfma_f32_16x16x32_bf16 v[38:41], v[162:165], v[196:199], v[38:41]
	v_mfma_f32_16x16x32_bf16 v[34:37], v[180:183], v[196:199], v[34:37]
	v_mfma_f32_16x16x32_bf16 v[22:25], v[162:165], v[204:207], v[22:25]
	v_mfma_f32_16x16x32_bf16 v[18:21], v[180:183], v[204:207], v[18:21]
	v_mfma_f32_16x16x32_bf16 v[6:9], v[162:165], v[212:215], v[6:9]
	v_mfma_f32_16x16x32_bf16 v[2:5], v[180:183], v[212:215], v[2:5]
	v_mfma_f32_16x16x32_bf16 v[54:57], v[176:179], v[192:195], v[54:57]
	v_mfma_f32_16x16x32_bf16 v[50:53], v[184:187], v[192:195], v[50:53]
	v_mfma_f32_16x16x32_bf16 v[38:41], v[176:179], v[200:203], v[38:41]
	v_mfma_f32_16x16x32_bf16 v[34:37], v[184:187], v[200:203], v[34:37]
	v_mfma_f32_16x16x32_bf16 v[22:25], v[176:179], v[208:211], v[22:25]
	v_mfma_f32_16x16x32_bf16 v[18:21], v[184:187], v[208:211], v[18:21]
	v_mfma_f32_16x16x32_bf16 v[6:9], v[176:179], v[216:219], v[6:9]
	v_mfma_f32_16x16x32_bf16 v[2:5], v[184:187], v[216:219], v[2:5]
	s_barrier
; #define PG8_STAGE(bufoff, gbase, voff) do { _Pragma("unroll") for (int _i = 0; _i < 2; ++_i) \
;         __builtin_amdgcn_global_load_lds((const unsigned*)((const char*)(gbase) + (voff)[_i]), (LAS unsigned*)(lds + (bufoff) + ldsw + _i * 8192), 16, 0, 0); } while (0)
; #define PG8_LDA(dst, b, h) do { _Pragma("unroll") for (int m = 0; m < 4; ++m) _Pragma("unroll") for (int k = 0; k < 2; ++k) dst[m][k] = *(const LAS bf16x8*)(lds + PG8_SA(b, h) + aoff + m * 2048 + k * 1024); } while (0)
; #define PG8_LDB(dst, b, h) do { _Pragma("unroll") for (int n = 0; n < 2; ++n) _Pragma("unroll") for (int k = 0; k < 2; ++k) dst[n][k] = *(const LAS bf16x8*)(lds + PG8_SB(b, h) + boff + n * 2048 + k * 1024); } while (0)
; #define PG8_MMA(ai, bj, At, Bt) do { __builtin_amdgcn_s_setprio(1); _Pragma("unroll") for (int m = 0; m < 4; ++m) _Pragma("unroll") for (int n = 0; n < 2; ++n) _Pragma("unroll") for (int k = 0; k < 2; ++k) \
;         acc[ai][bj][m][n] = __builtin_amdgcn_mfma_f32_16x16x32_bf16(Bt[n][k], At[m][k], acc[ai][bj][m][n], 0, 0, 0); __builtin_amdgcn_s_setprio(0); } while (0)
; #define PG8_WAIT_V(n) asm volatile("s_waitcnt vmcnt(" #n ")" ::: "memory")
; #define PG8_WAIT_L(n) asm volatile("s_waitcnt lgkmcnt(" #n ")" ::: "memory")
; #define PG8_BAR __builtin_amdgcn_s_barrier()
; #define PG8_SCHED __builtin_amdgcn_sched_barrier(0)
; template <class Epi, class Sched, int NSEG, int KK, int LDA, int LDB>
; __device__ __forceinline__ void gemm_phase(LAS unsigned char* lds, const Gemm g, const Sched& S, const Epi& E) {
;     ...
;             PG8_LDB(B0, 1, 0); PG8_LDB(B1, 1, 1); PG8_SCHED; PG8_LDA(At, 1, 0); PG8_STAGE(PG8_SA(0, 1), a2 + hstepA, voffA);
;             PG8_WAIT_V(8); PG8_WAIT_L(0); PG8_BAR; PG8_MMA(0, 0, At, B0); PG8_MMA(0, 1, At, B1); PG8_BAR; PG8_SCHED;
	s_setprio 0
	s_add_i32 s63, 0, 0x18000
	v_add_u32_e32 v0, s63, v156
	s_add_i32 s77, 0, 0x1c000
	ds_read_b128 v[130:133], v0
	ds_read_b128 v[134:137], v0 offset:1024
	ds_read_b128 v[138:141], v0 offset:2048
	ds_read_b128 v[158:161], v0 offset:3072
	v_add_u32_e32 v0, s77, v156
	ds_read_b128 v[162:165], v0
	ds_read_b128 v[176:179], v0 offset:1024
	ds_read_b128 v[180:183], v0 offset:2048
	ds_read_b128 v[184:187], v0 offset:3072
	s_add_u32 s50, s50, 0x40000
	s_addc_u32 s51, s51, 0
	s_mov_b32 m0, s26
	v_lshl_add_u64 v[224:225], s[50:51], 0, v[148:149]
	ds_read_b128 v[188:191], v157 offset:32768
	ds_read_b128 v[192:195], v157 offset:33792
	ds_read_b128 v[196:199], v157 offset:34816
	ds_read_b128 v[200:203], v157 offset:35840
	ds_read_b128 v[204:207], v157 offset:36864
	ds_read_b128 v[208:211], v157 offset:37888
	ds_read_b128 v[212:215], v157 offset:38912
	ds_read_b128 v[216:219], v157 offset:39936
	global_load_lds_dwordx4 v[224:225], off
	v_lshl_add_u64 v[224:225], s[50:51], 0, v[144:145]
	s_mov_b32 m0, s33
	s_nop 0
	global_load_lds_dwordx4 v[224:225], off
	s_waitcnt vmcnt(8)
	s_waitcnt lgkmcnt(0)
	s_barrier
	s_setprio 1
	v_mfma_f32_16x16x32_bf16 v[126:129], v[130:133], v[188:191], v[126:129]
	v_mfma_f32_16x16x32_bf16 v[122:125], v[138:141], v[188:191], v[122:125]
	v_mfma_f32_16x16x32_bf16 v[110:113], v[130:133], v[196:199], v[110:113]
	v_mfma_f32_16x16x32_bf16 v[106:109], v[138:141], v[196:199], v[106:109]
	v_mfma_f32_16x16x32_bf16 v[94:97], v[130:133], v[204:207], v[94:97]
	v_mfma_f32_16x16x32_bf16 v[90:93], v[138:141], v[204:207], v[90:93]
	v_mfma_f32_16x16x32_bf16 v[78:81], v[130:133], v[212:215], v[78:81]
	v_mfma_f32_16x16x32_bf16 v[74:77], v[138:141], v[212:215], v[74:77]
	v_mfma_f32_16x16x32_bf16 v[126:129], v[134:137], v[192:195], v[126:129]
	v_mfma_f32_16x16x32_bf16 v[122:125], v[158:161], v[192:195], v[122:125]
	v_mfma_f32_16x16x32_bf16 v[110:113], v[134:137], v[200:203], v[110:113]
	v_mfma_f32_16x16x32_bf16 v[106:109], v[158:161], v[200:203], v[106:109]
	v_mfma_f32_16x16x32_bf16 v[94:97], v[134:137], v[208:211], v[94:97]
	v_mfma_f32_16x16x32_bf16 v[90:93], v[158:161], v[208:211], v[90:93]
	v_mfma_f32_16x16x32_bf16 v[78:81], v[134:137], v[216:219], v[78:81]
	v_mfma_f32_16x16x32_bf16 v[74:77], v[158:161], v[216:219], v[74:77]
	s_setprio 0
	s_setprio 1
	v_mfma_f32_16x16x32_bf16 v[118:121], v[162:165], v[188:191], v[118:121]
	v_mfma_f32_16x16x32_bf16 v[114:117], v[180:183], v[188:191], v[114:117]
	v_mfma_f32_16x16x32_bf16 v[102:105], v[162:165], v[196:199], v[102:105]
	v_mfma_f32_16x16x32_bf16 v[98:101], v[180:183], v[196:199], v[98:101]
	v_mfma_f32_16x16x32_bf16 v[86:89], v[162:165], v[204:207], v[86:89]
	v_mfma_f32_16x16x32_bf16 v[82:85], v[180:183], v[204:207], v[82:85]
	v_mfma_f32_16x16x32_bf16 v[70:73], v[162:165], v[212:215], v[70:73]
	v_mfma_f32_16x16x32_bf16 v[66:69], v[180:183], v[212:215], v[66:69]
	v_mfma_f32_16x16x32_bf16 v[118:121], v[176:179], v[192:195], v[118:121]
	v_mfma_f32_16x16x32_bf16 v[114:117], v[184:187], v[192:195], v[114:117]
	v_mfma_f32_16x16x32_bf16 v[102:105], v[176:179], v[200:203], v[102:105]
	v_mfma_f32_16x16x32_bf16 v[98:101], v[184:187], v[200:203], v[98:101]
	v_mfma_f32_16x16x32_bf16 v[86:89], v[176:179], v[208:211], v[86:89]
	v_mfma_f32_16x16x32_bf16 v[82:85], v[184:187], v[208:211], v[82:85]
	v_mfma_f32_16x16x32_bf16 v[70:73], v[176:179], v[216:219], v[70:73]
	v_mfma_f32_16x16x32_bf16 v[66:69], v[184:187], v[216:219], v[66:69]
	s_barrier
; #define PG8_STAGE(bufoff, gbase, voff) do { _Pragma("unroll") for (int _i = 0; _i < 2; ++_i) \
;         __builtin_amdgcn_global_load_lds((const unsigned*)((const char*)(gbase) + (voff)[_i]), (LAS unsigned*)(lds + (bufoff) + ldsw + _i * 8192), 16, 0, 0); } while (0)
; #define PG8_LDA(dst, b, h) do { _Pragma("unroll") for (int m = 0; m < 4; ++m) _Pragma("unroll") for (int k = 0; k < 2; ++k) dst[m][k] = *(const LAS bf16x8*)(lds + PG8_SA(b, h) + aoff + m * 2048 + k * 1024); } while (0)
; #define PG8_MMA(ai, bj, At, Bt) do { __builtin_amdgcn_s_setprio(1); _Pragma("unroll") for (int m = 0; m < 4; ++m) _Pragma("unroll") for (int n = 0; n < 2; ++n) _Pragma("unroll") for (int k = 0; k < 2; ++k) \
;         acc[ai][bj][m][n] = __builtin_amdgcn_mfma_f32_16x16x32_bf16(Bt[n][k], At[m][k], acc[ai][bj][m][n], 0, 0, 0); __builtin_amdgcn_s_setprio(0); } while (0)
; #define PG8_WAIT_V(n) asm volatile("s_waitcnt vmcnt(" #n ")" ::: "memory")
; #define PG8_WAIT_L(n) asm volatile("s_waitcnt lgkmcnt(" #n ")" ::: "memory")
; #define PG8_BAR __builtin_amdgcn_s_barrier()
; #define PG8_SCHED __builtin_amdgcn_sched_barrier(0)
; template <class Epi, class Sched, int NSEG, int KK, int LDA, int LDB>
; __device__ __forceinline__ void gemm_phase(LAS unsigned char* lds, const Gemm g, const Sched& S, const Epi& E) {
;     ...
;             PG8_LDA(At, 1, 1); PG8_STAGE(PG8_SB(1, 0), b3, voffB); PG8_STAGE(PG8_SB(1, 1), b3 + hstepB, voffB); PG8_STAGE(PG8_SA(1, 0), a3, voffA);
;             PG8_WAIT_V(8); PG8_WAIT_L(0); PG8_BAR; PG8_MMA(1, 0, At, B0); PG8_MMA(1, 1, At, B1); PG8_BAR; PG8_SCHED;
;         }
;         if (wr == 0) PG8_BAR;
	s_setprio 0
	s_add_i32 s50, s63, s13
	v_lshl_add_u64 v[154:155], v[154:155], 0, s[28:29]
	s_mov_b32 m0, s50
	ds_read_b128 v[188:191], v157 offset:49152
	ds_read_b128 v[192:195], v157 offset:50176
	ds_read_b128 v[196:199], v157 offset:51200
	ds_read_b128 v[200:203], v157 offset:52224
	ds_read_b128 v[204:207], v157 offset:53248
	ds_read_b128 v[208:211], v157 offset:54272
	ds_read_b128 v[212:215], v157 offset:55296
	ds_read_b128 v[216:219], v157 offset:56320
	global_load_lds_dwordx4 v[154:155], off
	s_add_i32 m0, s50, 0x2000
	s_add_u32 s10, s10, 0x40080
	v_lshl_add_u64 v[154:155], v[166:167], 0, s[28:29]
	s_addc_u32 s11, s11, 0
	s_add_i32 s50, s77, s13
	global_load_lds_dwordx4 v[154:155], off
	v_lshl_add_u64 v[154:155], s[10:11], 0, v[146:147]
	s_mov_b32 m0, s50
	s_nop 0
	global_load_lds_dwordx4 v[154:155], off
	v_lshl_add_u64 v[154:155], s[10:11], 0, v[142:143]
	s_add_i32 m0, s50, 0x2000
	s_nop 0
	global_load_lds_dwordx4 v[154:155], off
	v_lshl_add_u64 v[154:155], v[220:221], 0, s[28:29]
	s_mov_b32 m0, s53
	s_nop 0
	global_load_lds_dwordx4 v[154:155], off
	v_lshl_add_u64 v[154:155], v[222:223], 0, s[28:29]
	s_mov_b32 m0, s54
	s_nop 0
	global_load_lds_dwordx4 v[154:155], off
	s_waitcnt vmcnt(8)
	s_waitcnt lgkmcnt(0)
	s_barrier
	s_setprio 1
	v_mfma_f32_16x16x32_bf16 v[62:65], v[130:133], v[188:191], v[62:65]
	v_mfma_f32_16x16x32_bf16 v[58:61], v[138:141], v[188:191], v[58:61]
	v_mfma_f32_16x16x32_bf16 v[46:49], v[130:133], v[196:199], v[46:49]
	v_mfma_f32_16x16x32_bf16 v[42:45], v[138:141], v[196:199], v[42:45]
	v_mfma_f32_16x16x32_bf16 v[30:33], v[130:133], v[204:207], v[30:33]
	v_mfma_f32_16x16x32_bf16 v[26:29], v[138:141], v[204:207], v[26:29]
	v_mfma_f32_16x16x32_bf16 v[14:17], v[130:133], v[212:215], v[14:17]
	v_mfma_f32_16x16x32_bf16 v[10:13], v[138:141], v[212:215], v[10:13]
	v_mfma_f32_16x16x32_bf16 v[62:65], v[134:137], v[192:195], v[62:65]
	v_mfma_f32_16x16x32_bf16 v[58:61], v[158:161], v[192:195], v[58:61]
	v_mfma_f32_16x16x32_bf16 v[46:49], v[134:137], v[200:203], v[46:49]
	v_mfma_f32_16x16x32_bf16 v[42:45], v[158:161], v[200:203], v[42:45]
	v_mfma_f32_16x16x32_bf16 v[30:33], v[134:137], v[208:211], v[30:33]
	v_mfma_f32_16x16x32_bf16 v[26:29], v[158:161], v[208:211], v[26:29]
	v_mfma_f32_16x16x32_bf16 v[14:17], v[134:137], v[216:219], v[14:17]
	v_mfma_f32_16x16x32_bf16 v[10:13], v[158:161], v[216:219], v[10:13]
	s_setprio 0
	s_setprio 1
	v_mfma_f32_16x16x32_bf16 v[54:57], v[162:165], v[188:191], v[54:57]
	v_mfma_f32_16x16x32_bf16 v[50:53], v[180:183], v[188:191], v[50:53]
	v_mfma_f32_16x16x32_bf16 v[38:41], v[162:165], v[196:199], v[38:41]
	v_mfma_f32_16x16x32_bf16 v[34:37], v[180:183], v[196:199], v[34:37]
	v_mfma_f32_16x16x32_bf16 v[22:25], v[162:165], v[204:207], v[22:25]
	v_mfma_f32_16x16x32_bf16 v[18:21], v[180:183], v[204:207], v[18:21]
	v_mfma_f32_16x16x32_bf16 v[6:9], v[162:165], v[212:215], v[6:9]
	v_mfma_f32_16x16x32_bf16 v[2:5], v[180:183], v[212:215], v[2:5]
	v_mfma_f32_16x16x32_bf16 v[54:57], v[176:179], v[192:195], v[54:57]
	v_mfma_f32_16x16x32_bf16 v[50:53], v[184:187], v[192:195], v[50:53]
	v_mfma_f32_16x16x32_bf16 v[38:41], v[176:179], v[200:203], v[38:41]
	v_mfma_f32_16x16x32_bf16 v[34:37], v[184:187], v[200:203], v[34:37]
	v_mfma_f32_16x16x32_bf16 v[22:25], v[176:179], v[208:211], v[22:25]
	v_mfma_f32_16x16x32_bf16 v[18:21], v[184:187], v[208:211], v[18:21]
	v_mfma_f32_16x16x32_bf16 v[6:9], v[176:179], v[216:219], v[6:9]
	v_mfma_f32_16x16x32_bf16 v[2:5], v[184:187], v[216:219], v[2:5]
	s_barrier
	s_setprio 0
	s_add_i32 s62, s62, 2
	s_add_u32 s40, s40, 0x100
	s_addc_u32 s41, s41, 0
	s_add_u32 s60, s60, 0x100
	s_addc_u32 s61, s61, 0
	s_cmp_gt_u32 s62, 13
	s_cbranch_scc0 .LBB0_388
	s_mov_b32 s101, 1
	s_and_b64 vcc, exec, s[24:25]
	s_cbranch_vccz .LBB0_391
	s_barrier

; #define PG8_STAGE(bufoff, gbase, voff) do { _Pragma("unroll") for (int _i = 0; _i < 2; ++_i) \
;         __builtin_amdgcn_global_load_lds((const unsigned*)((const char*)(gbase) + (voff)[_i]), (LAS unsigned*)(lds + (bufoff) + ldsw + _i * 8192), 16, 0, 0); } while (0)
; #define PG8_LDA(dst, b, h) do { _Pragma("unroll") for (int m = 0; m < 4; ++m) _Pragma("unroll") for (int k = 0; k < 2; ++k) dst[m][k] = *(const LAS bf16x8*)(lds + PG8_SA(b, h) + aoff + m * 2048 + k * 1024); } while (0)
; #define PG8_MMA(ai, bj, At, Bt) do { __builtin_amdgcn_s_setprio(1); _Pragma("unroll") for (int m = 0; m < 4; ++m) _Pragma("unroll") for (int n = 0; n < 2; ++n) _Pragma("unroll") for (int k = 0; k < 2; ++k) \
;         acc[ai][bj][m][n] = __builtin_amdgcn_mfma_f32_16x16x32_bf16(Bt[n][k], At[m][k], acc[ai][bj][m][n], 0, 0, 0); __builtin_amdgcn_s_setprio(0); } while (0)
; #define PG8_WAIT_V(n) asm volatile("s_waitcnt vmcnt(" #n ")" ::: "memory")
; #define PG8_WAIT_L(n) asm volatile("s_waitcnt lgkmcnt(" #n ")" ::: "memory")
; #define PG8_BAR __builtin_amdgcn_s_barrier()
; #define PG8_SCHED __builtin_amdgcn_sched_barrier(0)
; template <class Epi, class Sched, int NSEG, int KK, int LDA, int LDB>
; __device__ __forceinline__ void gemm_phase(LAS unsigned char* lds, const Gemm g, const Sched& S, const Epi& E) {
;     ...
;             PG8_WAIT_V(8); PG8_WAIT_L(0); PG8_BAR; PG8_MMA(0, 0, At, B0); PG8_MMA(0, 1, At, B1); PG8_BAR; PG8_SCHED;
;             PG8_LDA(At, 0, 1); PG8_STAGE(PG8_SB(0, 0), b2, voffB); PG8_STAGE(PG8_SB(0, 1), b2 + hstepB, voffB); PG8_STAGE(PG8_SA(0, 0), a2, voffA);
;             PG8_WAIT_V(8); PG8_WAIT_L(0); PG8_BAR; PG8_MMA(1, 0, At, B0); PG8_MMA(1, 1, At, B1); PG8_BAR; PG8_SCHED;
.Lskw_1_1:
	s_waitcnt lgkmcnt(0)
	s_barrier
	s_setprio 1
	v_mfma_f32_16x16x32_bf16 v[126:129], v[130:133], v[184:187], v[126:129]
	v_mfma_f32_16x16x32_bf16 v[122:125], v[138:141], v[184:187], v[122:125]
	v_mfma_f32_16x16x32_bf16 v[118:121], v[130:133], v[192:195], v[118:121]
	v_mfma_f32_16x16x32_bf16 v[114:117], v[138:141], v[192:195], v[114:117]
	v_mfma_f32_16x16x32_bf16 v[102:105], v[130:133], v[200:203], v[102:105]
	v_mfma_f32_16x16x32_bf16 v[98:101], v[138:141], v[200:203], v[98:101]
	v_mfma_f32_16x16x32_bf16 v[86:89], v[130:133], v[208:211], v[86:89]
	v_mfma_f32_16x16x32_bf16 v[82:85], v[138:141], v[208:211], v[82:85]
	v_mfma_f32_16x16x32_bf16 v[126:129], v[134:137], v[188:191], v[126:129]
	v_mfma_f32_16x16x32_bf16 v[122:125], v[156:159], v[188:191], v[122:125]
	v_mfma_f32_16x16x32_bf16 v[118:121], v[134:137], v[196:199], v[118:121]
	v_mfma_f32_16x16x32_bf16 v[114:117], v[156:159], v[196:199], v[114:117]
	v_mfma_f32_16x16x32_bf16 v[102:105], v[134:137], v[204:207], v[102:105]
	v_mfma_f32_16x16x32_bf16 v[98:101], v[156:159], v[204:207], v[98:101]
	v_mfma_f32_16x16x32_bf16 v[86:89], v[134:137], v[212:215], v[86:89]
	v_mfma_f32_16x16x32_bf16 v[82:85], v[156:159], v[212:215], v[82:85]
	s_setprio 0
	s_setprio 1
	v_mfma_f32_16x16x32_bf16 v[110:113], v[160:163], v[184:187], v[110:113]
	v_mfma_f32_16x16x32_bf16 v[106:109], v[176:179], v[184:187], v[106:109]
	v_mfma_f32_16x16x32_bf16 v[94:97], v[160:163], v[192:195], v[94:97]
	v_mfma_f32_16x16x32_bf16 v[90:93], v[176:179], v[192:195], v[90:93]
	v_mfma_f32_16x16x32_bf16 v[78:81], v[160:163], v[200:203], v[78:81]
	v_mfma_f32_16x16x32_bf16 v[74:77], v[176:179], v[200:203], v[74:77]
	v_mfma_f32_16x16x32_bf16 v[70:73], v[160:163], v[208:211], v[70:73]
	v_mfma_f32_16x16x32_bf16 v[66:69], v[176:179], v[208:211], v[66:69]
	v_mfma_f32_16x16x32_bf16 v[110:113], v[164:167], v[188:191], v[110:113]
	v_mfma_f32_16x16x32_bf16 v[106:109], v[180:183], v[188:191], v[106:109]
	v_mfma_f32_16x16x32_bf16 v[94:97], v[164:167], v[196:199], v[94:97]
	v_mfma_f32_16x16x32_bf16 v[90:93], v[180:183], v[196:199], v[90:93]
	v_mfma_f32_16x16x32_bf16 v[78:81], v[164:167], v[204:207], v[78:81]
	v_mfma_f32_16x16x32_bf16 v[74:77], v[180:183], v[204:207], v[74:77]
	v_mfma_f32_16x16x32_bf16 v[70:73], v[164:167], v[212:215], v[70:73]
	v_mfma_f32_16x16x32_bf16 v[66:69], v[180:183], v[212:215], v[66:69]
	s_barrier
	s_setprio 0
	s_add_i32 s63, s63, s23
	v_lshl_add_u64 v[216:217], s[10:11], 0, v[146:147]
	s_mov_b32 m0, s63
	ds_read_b128 v[184:187], v155 offset:16384
	ds_read_b128 v[188:191], v155 offset:17408
	ds_read_b128 v[192:195], v155 offset:18432
	ds_read_b128 v[196:199], v155 offset:19456
	ds_read_b128 v[200:203], v155 offset:20480
	ds_read_b128 v[204:207], v155 offset:21504
	ds_read_b128 v[208:211], v155 offset:22528
	ds_read_b128 v[212:215], v155 offset:23552
	global_load_lds_dwordx4 v[216:217], off
	s_add_i32 m0, s63, 0x2000
	s_add_u32 s94, s10, 0x40000
	v_lshl_add_u64 v[218:219], s[10:11], 0, v[142:143]
	s_addc_u32 s95, s11, 0
	s_add_i32 s63, s77, s23
	global_load_lds_dwordx4 v[218:219], off
	v_lshl_add_u64 v[220:221], s[94:95], 0, v[146:147]
	s_mov_b32 m0, s63
	v_lshl_add_u64 v[222:223], s[50:51], 0, v[144:145]
	global_load_lds_dwordx4 v[220:221], off
	v_lshl_add_u64 v[220:221], s[94:95], 0, v[142:143]
	s_add_i32 m0, s63, 0x2000
	s_nop 0
	global_load_lds_dwordx4 v[220:221], off
	v_lshl_add_u64 v[220:221], s[50:51], 0, v[148:149]
	s_mov_b32 m0, s26
	s_nop 0
	global_load_lds_dwordx4 v[220:221], off
	s_mov_b32 m0, s33
	s_nop 0
	global_load_lds_dwordx4 v[222:223], off
	s_cmp_lg_u32 s101, 0
	s_cbranch_scc1 .Lskw_1_2
	s_waitcnt vmcnt(8)
.Lskw_1_2:
	s_mov_b32 s101, 0
	s_waitcnt lgkmcnt(0)
	s_barrier
	s_setprio 1
	v_mfma_f32_16x16x32_bf16 v[62:65], v[130:133], v[184:187], v[62:65]
	v_mfma_f32_16x16x32_bf16 v[58:61], v[138:141], v[184:187], v[58:61]
	v_mfma_f32_16x16x32_bf16 v[54:57], v[130:133], v[192:195], v[54:57]
	v_mfma_f32_16x16x32_bf16 v[50:53], v[138:141], v[192:195], v[50:53]
	v_mfma_f32_16x16x32_bf16 v[38:41], v[130:133], v[200:203], v[38:41]
	v_mfma_f32_16x16x32_bf16 v[34:37], v[138:141], v[200:203], v[34:37]
	v_mfma_f32_16x16x32_bf16 v[22:25], v[130:133], v[208:211], v[22:25]
	v_mfma_f32_16x16x32_bf16 v[18:21], v[138:141], v[208:211], v[18:21]
	v_mfma_f32_16x16x32_bf16 v[62:65], v[134:137], v[188:191], v[62:65]
	v_mfma_f32_16x16x32_bf16 v[58:61], v[156:159], v[188:191], v[58:61]
	v_mfma_f32_16x16x32_bf16 v[54:57], v[134:137], v[196:199], v[54:57]
	v_mfma_f32_16x16x32_bf16 v[50:53], v[156:159], v[196:199], v[50:53]
	v_mfma_f32_16x16x32_bf16 v[38:41], v[134:137], v[204:207], v[38:41]
	v_mfma_f32_16x16x32_bf16 v[34:37], v[156:159], v[204:207], v[34:37]
	v_mfma_f32_16x16x32_bf16 v[22:25], v[134:137], v[212:215], v[22:25]
	v_mfma_f32_16x16x32_bf16 v[18:21], v[156:159], v[212:215], v[18:21]
	s_setprio 0
	s_setprio 1
	v_mfma_f32_16x16x32_bf16 v[46:49], v[160:163], v[184:187], v[46:49]
	v_mfma_f32_16x16x32_bf16 v[42:45], v[176:179], v[184:187], v[42:45]
	v_mfma_f32_16x16x32_bf16 v[30:33], v[160:163], v[192:195], v[30:33]
	v_mfma_f32_16x16x32_bf16 v[26:29], v[176:179], v[192:195], v[26:29]
	v_mfma_f32_16x16x32_bf16 v[14:17], v[160:163], v[200:203], v[14:17]
	v_mfma_f32_16x16x32_bf16 v[10:13], v[176:179], v[200:203], v[10:13]
	v_mfma_f32_16x16x32_bf16 v[6:9], v[160:163], v[208:211], v[6:9]
	v_mfma_f32_16x16x32_bf16 v[2:5], v[176:179], v[208:211], v[2:5]
	v_mfma_f32_16x16x32_bf16 v[46:49], v[164:167], v[188:191], v[46:49]
	v_mfma_f32_16x16x32_bf16 v[42:45], v[180:183], v[188:191], v[42:45]
	v_mfma_f32_16x16x32_bf16 v[30:33], v[164:167], v[196:199], v[30:33]
	v_mfma_f32_16x16x32_bf16 v[26:29], v[180:183], v[196:199], v[26:29]
	v_mfma_f32_16x16x32_bf16 v[14:17], v[164:167], v[204:207], v[14:17]
	v_mfma_f32_16x16x32_bf16 v[10:13], v[180:183], v[204:207], v[10:13]
	v_mfma_f32_16x16x32_bf16 v[6:9], v[164:167], v[212:215], v[6:9]
	v_mfma_f32_16x16x32_bf16 v[2:5], v[180:183], v[212:215], v[2:5]
	s_barrier
; #define PG8_STAGE(bufoff, gbase, voff) do { _Pragma("unroll") for (int _i = 0; _i < 2; ++_i) \
;         __builtin_amdgcn_global_load_lds((const unsigned*)((const char*)(gbase) + (voff)[_i]), (LAS unsigned*)(lds + (bufoff) + ldsw + _i * 8192), 16, 0, 0); } while (0)
; #define PG8_LDA(dst, b, h) do { _Pragma("unroll") for (int m = 0; m < 4; ++m) _Pragma("unroll") for (int k = 0; k < 2; ++k) dst[m][k] = *(const LAS bf16x8*)(lds + PG8_SA(b, h) + aoff + m * 2048 + k * 1024); } while (0)
; #define PG8_LDB(dst, b, h) do { _Pragma("unroll") for (int n = 0; n < 2; ++n) _Pragma("unroll") for (int k = 0; k < 2; ++k) dst[n][k] = *(const LAS bf16x8*)(lds + PG8_SB(b, h) + boff + n * 2048 + k * 1024); } while (0)
; #define PG8_MMA(ai, bj, At, Bt) do { __builtin_amdgcn_s_setprio(1); _Pragma("unroll") for (int m = 0; m < 4; ++m) _Pragma("unroll") for (int n = 0; n < 2; ++n) _Pragma("unroll") for (int k = 0; k < 2; ++k) \
;         acc[ai][bj][m][n] = __builtin_amdgcn_mfma_f32_16x16x32_bf16(Bt[n][k], At[m][k], acc[ai][bj][m][n], 0, 0, 0); __builtin_amdgcn_s_setprio(0); } while (0)
; #define PG8_WAIT_V(n) asm volatile("s_waitcnt vmcnt(" #n ")" ::: "memory")
; #define PG8_WAIT_L(n) asm volatile("s_waitcnt lgkmcnt(" #n ")" ::: "memory")
; #define PG8_BAR __builtin_amdgcn_s_barrier()
; #define PG8_SCHED __builtin_amdgcn_sched_barrier(0)
; template <class Epi, class Sched, int NSEG, int KK, int LDA, int LDB>
; __device__ __forceinline__ void gemm_phase(LAS unsigned char* lds, const Gemm g, const Sched& S, const Epi& E) {
;     ...
;             PG8_LDB(B0, 1, 0); PG8_LDB(B1, 1, 1); PG8_SCHED; PG8_LDA(At, 1, 0); PG8_STAGE(PG8_SA(0, 1), a2 + hstepA, voffA);
;             PG8_WAIT_V(8); PG8_WAIT_L(0); PG8_BAR; PG8_MMA(0, 0, At, B0); PG8_MMA(0, 1, At, B1); PG8_BAR; PG8_SCHED;
	s_setprio 0
	s_add_i32 s63, 0, 0x18000
	v_add_u32_e32 v0, s63, v154
	s_add_i32 s77, 0, 0x1c000
	ds_read_b128 v[130:133], v0
	ds_read_b128 v[134:137], v0 offset:1024
	ds_read_b128 v[138:141], v0 offset:2048
	ds_read_b128 v[156:159], v0 offset:3072
	v_add_u32_e32 v0, s77, v154
	ds_read_b128 v[160:163], v0
	ds_read_b128 v[164:167], v0 offset:1024
	ds_read_b128 v[176:179], v0 offset:2048
	ds_read_b128 v[180:183], v0 offset:3072
	s_add_u32 s50, s50, 0x40000
	s_addc_u32 s51, s51, 0
	s_mov_b32 m0, s38
	v_lshl_add_u64 v[224:225], s[50:51], 0, v[148:149]
	ds_read_b128 v[184:187], v155 offset:32768
	ds_read_b128 v[188:191], v155 offset:33792
	ds_read_b128 v[192:195], v155 offset:34816
	ds_read_b128 v[196:199], v155 offset:35840
	ds_read_b128 v[200:203], v155 offset:36864
	ds_read_b128 v[204:207], v155 offset:37888
	ds_read_b128 v[208:211], v155 offset:38912
	ds_read_b128 v[212:215], v155 offset:39936
	global_load_lds_dwordx4 v[224:225], off
	v_lshl_add_u64 v[224:225], s[50:51], 0, v[144:145]
	s_mov_b32 m0, s39
	s_nop 0
	global_load_lds_dwordx4 v[224:225], off
	s_waitcnt vmcnt(8)
	s_waitcnt lgkmcnt(0)
	s_barrier
	s_setprio 1
	v_mfma_f32_16x16x32_bf16 v[126:129], v[130:133], v[184:187], v[126:129]
	v_mfma_f32_16x16x32_bf16 v[122:125], v[138:141], v[184:187], v[122:125]
	v_mfma_f32_16x16x32_bf16 v[118:121], v[130:133], v[192:195], v[118:121]
	v_mfma_f32_16x16x32_bf16 v[114:117], v[138:141], v[192:195], v[114:117]
	v_mfma_f32_16x16x32_bf16 v[102:105], v[130:133], v[200:203], v[102:105]
	v_mfma_f32_16x16x32_bf16 v[98:101], v[138:141], v[200:203], v[98:101]
	v_mfma_f32_16x16x32_bf16 v[86:89], v[130:133], v[208:211], v[86:89]
	v_mfma_f32_16x16x32_bf16 v[82:85], v[138:141], v[208:211], v[82:85]
	v_mfma_f32_16x16x32_bf16 v[126:129], v[134:137], v[188:191], v[126:129]
	v_mfma_f32_16x16x32_bf16 v[122:125], v[156:159], v[188:191], v[122:125]
	v_mfma_f32_16x16x32_bf16 v[118:121], v[134:137], v[196:199], v[118:121]
	v_mfma_f32_16x16x32_bf16 v[114:117], v[156:159], v[196:199], v[114:117]
	v_mfma_f32_16x16x32_bf16 v[102:105], v[134:137], v[204:207], v[102:105]
	v_mfma_f32_16x16x32_bf16 v[98:101], v[156:159], v[204:207], v[98:101]
	v_mfma_f32_16x16x32_bf16 v[86:89], v[134:137], v[212:215], v[86:89]
	v_mfma_f32_16x16x32_bf16 v[82:85], v[156:159], v[212:215], v[82:85]
	s_setprio 0
	s_setprio 1
	v_mfma_f32_16x16x32_bf16 v[110:113], v[160:163], v[184:187], v[110:113]
	v_mfma_f32_16x16x32_bf16 v[106:109], v[176:179], v[184:187], v[106:109]
	v_mfma_f32_16x16x32_bf16 v[94:97], v[160:163], v[192:195], v[94:97]
	v_mfma_f32_16x16x32_bf16 v[90:93], v[176:179], v[192:195], v[90:93]
	v_mfma_f32_16x16x32_bf16 v[78:81], v[160:163], v[200:203], v[78:81]
	v_mfma_f32_16x16x32_bf16 v[74:77], v[176:179], v[200:203], v[74:77]
	v_mfma_f32_16x16x32_bf16 v[70:73], v[160:163], v[208:211], v[70:73]
	v_mfma_f32_16x16x32_bf16 v[66:69], v[176:179], v[208:211], v[66:69]
	v_mfma_f32_16x16x32_bf16 v[110:113], v[164:167], v[188:191], v[110:113]
	v_mfma_f32_16x16x32_bf16 v[106:109], v[180:183], v[188:191], v[106:109]
	v_mfma_f32_16x16x32_bf16 v[94:97], v[164:167], v[196:199], v[94:97]
	v_mfma_f32_16x16x32_bf16 v[90:93], v[180:183], v[196:199], v[90:93]
	v_mfma_f32_16x16x32_bf16 v[78:81], v[164:167], v[204:207], v[78:81]
	v_mfma_f32_16x16x32_bf16 v[74:77], v[180:183], v[204:207], v[74:77]
	v_mfma_f32_16x16x32_bf16 v[70:73], v[164:167], v[212:215], v[70:73]
	v_mfma_f32_16x16x32_bf16 v[66:69], v[180:183], v[212:215], v[66:69]
	s_barrier
; #define PG8_STAGE(bufoff, gbase, voff) do { _Pragma("unroll") for (int _i = 0; _i < 2; ++_i) \
;         __builtin_amdgcn_global_load_lds((const unsigned*)((const char*)(gbase) + (voff)[_i]), (LAS unsigned*)(lds + (bufoff) + ldsw + _i * 8192), 16, 0, 0); } while (0)
; #define PG8_LDA(dst, b, h) do { _Pragma("unroll") for (int m = 0; m < 4; ++m) _Pragma("unroll") for (int k = 0; k < 2; ++k) dst[m][k] = *(const LAS bf16x8*)(lds + PG8_SA(b, h) + aoff + m * 2048 + k * 1024); } while (0)
; #define PG8_MMA(ai, bj, At, Bt) do { __builtin_amdgcn_s_setprio(1); _Pragma("unroll") for (int m = 0; m < 4; ++m) _Pragma("unroll") for (int n = 0; n < 2; ++n) _Pragma("unroll") for (int k = 0; k < 2; ++k) \
;         acc[ai][bj][m][n] = __builtin_amdgcn_mfma_f32_16x16x32_bf16(Bt[n][k], At[m][k], acc[ai][bj][m][n], 0, 0, 0); __builtin_amdgcn_s_setprio(0); } while (0)
; #define PG8_WAIT_V(n) asm volatile("s_waitcnt vmcnt(" #n ")" ::: "memory")
; #define PG8_WAIT_L(n) asm volatile("s_waitcnt lgkmcnt(" #n ")" ::: "memory")
; #define PG8_BAR __builtin_amdgcn_s_barrier()
; #define PG8_SCHED __builtin_amdgcn_sched_barrier(0)
; template <class Epi, class Sched, int NSEG, int KK, int LDA, int LDB>
; __device__ __forceinline__ void gemm_phase(LAS unsigned char* lds, const Gemm g, const Sched& S, const Epi& E) {
;     ...
;             PG8_LDA(At, 1, 1); PG8_STAGE(PG8_SB(1, 0), b3, voffB); PG8_STAGE(PG8_SB(1, 1), b3 + hstepB, voffB); PG8_STAGE(PG8_SA(1, 0), a3, voffA);
;             PG8_WAIT_V(8); PG8_WAIT_L(0); PG8_BAR; PG8_MMA(1, 0, At, B0); PG8_MMA(1, 1, At, B1); PG8_BAR; PG8_SCHED;
;         }
;         if (wr == 0) PG8_BAR;
	s_setprio 0
	s_add_i32 s50, s63, s23
	v_lshl_add_u64 v[216:217], v[216:217], 0, s[28:29]
	s_mov_b32 m0, s50
	ds_read_b128 v[184:187], v155 offset:49152
	ds_read_b128 v[188:191], v155 offset:50176
	ds_read_b128 v[192:195], v155 offset:51200
	ds_read_b128 v[196:199], v155 offset:52224
	ds_read_b128 v[200:203], v155 offset:53248
	ds_read_b128 v[204:207], v155 offset:54272
	ds_read_b128 v[208:211], v155 offset:55296
	ds_read_b128 v[212:215], v155 offset:56320
	global_load_lds_dwordx4 v[216:217], off
	s_add_i32 m0, s50, 0x2000
	s_add_u32 s10, s10, 0x40080
	v_lshl_add_u64 v[216:217], v[218:219], 0, s[28:29]
	s_addc_u32 s11, s11, 0
	s_add_i32 s50, s77, s23
	global_load_lds_dwordx4 v[216:217], off
	v_lshl_add_u64 v[216:217], s[10:11], 0, v[146:147]
	s_mov_b32 m0, s50
	s_nop 0
	global_load_lds_dwordx4 v[216:217], off
	v_lshl_add_u64 v[216:217], s[10:11], 0, v[142:143]
	s_add_i32 m0, s50, 0x2000
	s_nop 0
	global_load_lds_dwordx4 v[216:217], off
	v_lshl_add_u64 v[216:217], v[220:221], 0, s[28:29]
	s_mov_b32 m0, s53
	s_nop 0
	global_load_lds_dwordx4 v[216:217], off
	v_lshl_add_u64 v[216:217], v[222:223], 0, s[28:29]
	s_mov_b32 m0, s54
	s_nop 0
	global_load_lds_dwordx4 v[216:217], off
	s_waitcnt vmcnt(8)
	s_waitcnt lgkmcnt(0)
	s_barrier
	s_setprio 1
	v_mfma_f32_16x16x32_bf16 v[62:65], v[130:133], v[184:187], v[62:65]
	v_mfma_f32_16x16x32_bf16 v[58:61], v[138:141], v[184:187], v[58:61]
	v_mfma_f32_16x16x32_bf16 v[54:57], v[130:133], v[192:195], v[54:57]
	v_mfma_f32_16x16x32_bf16 v[50:53], v[138:141], v[192:195], v[50:53]
	v_mfma_f32_16x16x32_bf16 v[38:41], v[130:133], v[200:203], v[38:41]
	v_mfma_f32_16x16x32_bf16 v[34:37], v[138:141], v[200:203], v[34:37]
	v_mfma_f32_16x16x32_bf16 v[22:25], v[130:133], v[208:211], v[22:25]
	v_mfma_f32_16x16x32_bf16 v[18:21], v[138:141], v[208:211], v[18:21]
	v_mfma_f32_16x16x32_bf16 v[62:65], v[134:137], v[188:191], v[62:65]
	v_mfma_f32_16x16x32_bf16 v[58:61], v[156:159], v[188:191], v[58:61]
	v_mfma_f32_16x16x32_bf16 v[54:57], v[134:137], v[196:199], v[54:57]
	v_mfma_f32_16x16x32_bf16 v[50:53], v[156:159], v[196:199], v[50:53]
	v_mfma_f32_16x16x32_bf16 v[38:41], v[134:137], v[204:207], v[38:41]
	v_mfma_f32_16x16x32_bf16 v[34:37], v[156:159], v[204:207], v[34:37]
	v_mfma_f32_16x16x32_bf16 v[22:25], v[134:137], v[212:215], v[22:25]
	v_mfma_f32_16x16x32_bf16 v[18:21], v[156:159], v[212:215], v[18:21]
	s_setprio 0
	s_setprio 1
	v_mfma_f32_16x16x32_bf16 v[46:49], v[160:163], v[184:187], v[46:49]
	v_mfma_f32_16x16x32_bf16 v[42:45], v[176:179], v[184:187], v[42:45]
	v_mfma_f32_16x16x32_bf16 v[30:33], v[160:163], v[192:195], v[30:33]
	v_mfma_f32_16x16x32_bf16 v[26:29], v[176:179], v[192:195], v[26:29]
	v_mfma_f32_16x16x32_bf16 v[14:17], v[160:163], v[200:203], v[14:17]
	v_mfma_f32_16x16x32_bf16 v[10:13], v[176:179], v[200:203], v[10:13]
	v_mfma_f32_16x16x32_bf16 v[6:9], v[160:163], v[208:211], v[6:9]
	v_mfma_f32_16x16x32_bf16 v[2:5], v[176:179], v[208:211], v[2:5]
	v_mfma_f32_16x16x32_bf16 v[46:49], v[164:167], v[188:191], v[46:49]
	v_mfma_f32_16x16x32_bf16 v[42:45], v[180:183], v[188:191], v[42:45]
	v_mfma_f32_16x16x32_bf16 v[30:33], v[164:167], v[196:199], v[30:33]
	v_mfma_f32_16x16x32_bf16 v[26:29], v[180:183], v[196:199], v[26:29]
	v_mfma_f32_16x16x32_bf16 v[14:17], v[164:167], v[204:207], v[14:17]
	v_mfma_f32_16x16x32_bf16 v[10:13], v[180:183], v[204:207], v[10:13]
	v_mfma_f32_16x16x32_bf16 v[6:9], v[164:167], v[212:215], v[6:9]
	v_mfma_f32_16x16x32_bf16 v[2:5], v[180:183], v[212:215], v[2:5]
	s_barrier
	s_setprio 0
	s_add_i32 s62, s62, 2
	s_add_u32 s48, s48, 0x100
	s_addc_u32 s49, s49, 0
	s_add_u32 s60, s60, 0x100
	s_addc_u32 s61, s61, 0
	s_cmp_gt_u32 s62, 13
	s_cbranch_scc0 .LBB0_677
	s_mov_b32 s101, 1
	s_and_b64 vcc, exec, s[8:9]
	s_cbranch_vccz .LBB0_680
	s_barrier

; #define PG8_STAGE(bufoff, gbase, voff) do { _Pragma("unroll") for (int _i = 0; _i < 2; ++_i) \
;         __builtin_amdgcn_global_load_lds((const unsigned*)((const char*)(gbase) + (voff)[_i]), (LAS unsigned*)(lds + (bufoff) + ldsw + _i * 8192), 16, 0, 0); } while (0)
; #define PG8_LDA(dst, b, h) do { _Pragma("unroll") for (int m = 0; m < 4; ++m) _Pragma("unroll") for (int k = 0; k < 2; ++k) dst[m][k] = *(const LAS bf16x8*)(lds + PG8_SA(b, h) + aoff + m * 2048 + k * 1024); } while (0)
; #define PG8_MMA(ai, bj, At, Bt) do { __builtin_amdgcn_s_setprio(1); _Pragma("unroll") for (int m = 0; m < 4; ++m) _Pragma("unroll") for (int n = 0; n < 2; ++n) _Pragma("unroll") for (int k = 0; k < 2; ++k) \
;         acc[ai][bj][m][n] = __builtin_amdgcn_mfma_f32_16x16x32_bf16(Bt[n][k], At[m][k], acc[ai][bj][m][n], 0, 0, 0); __builtin_amdgcn_s_setprio(0); } while (0)
; #define PG8_WAIT_V(n) asm volatile("s_waitcnt vmcnt(" #n ")" ::: "memory")
; #define PG8_WAIT_L(n) asm volatile("s_waitcnt lgkmcnt(" #n ")" ::: "memory")
; #define PG8_BAR __builtin_amdgcn_s_barrier()
; #define PG8_SCHED __builtin_amdgcn_sched_barrier(0)
; template <class Epi, class Sched, int NSEG, int KK, int LDA, int LDB>
; __device__ __forceinline__ void gemm_phase(LAS unsigned char* lds, const Gemm g, const Sched& S, const Epi& E) {
;     ...
;             PG8_WAIT_V(8); PG8_WAIT_L(0); PG8_BAR; PG8_MMA(0, 0, At, B0); PG8_MMA(0, 1, At, B1); PG8_BAR; PG8_SCHED;
;             PG8_LDA(At, 0, 1); PG8_STAGE(PG8_SB(0, 0), b2, voffB); PG8_STAGE(PG8_SB(0, 1), b2 + hstepB, voffB); PG8_STAGE(PG8_SA(0, 0), a2, voffA);
;             PG8_WAIT_V(8); PG8_WAIT_L(0); PG8_BAR; PG8_MMA(1, 0, At, B0); PG8_MMA(1, 1, At, B1); PG8_BAR; PG8_SCHED;
.Lskw_2_1:
	s_waitcnt lgkmcnt(0)
	s_barrier
	s_setprio 1
	v_mfma_f32_16x16x32_bf16 v[126:129], v[140:143], v[180:183], v[126:129]
	v_mfma_f32_16x16x32_bf16 v[122:125], v[148:151], v[180:183], v[122:125]
	v_mfma_f32_16x16x32_bf16 v[118:121], v[140:143], v[188:191], v[118:121]
	v_mfma_f32_16x16x32_bf16 v[114:117], v[148:151], v[188:191], v[114:117]
	v_mfma_f32_16x16x32_bf16 v[110:113], v[140:143], v[196:199], v[110:113]
	v_mfma_f32_16x16x32_bf16 v[106:109], v[148:151], v[196:199], v[106:109]
	v_mfma_f32_16x16x32_bf16 v[102:105], v[140:143], v[204:207], v[102:105]
	v_mfma_f32_16x16x32_bf16 v[98:101], v[148:151], v[204:207], v[98:101]
	v_mfma_f32_16x16x32_bf16 v[126:129], v[144:147], v[184:187], v[126:129]
	v_mfma_f32_16x16x32_bf16 v[122:125], v[152:155], v[184:187], v[122:125]
	v_mfma_f32_16x16x32_bf16 v[118:121], v[144:147], v[192:195], v[118:121]
	v_mfma_f32_16x16x32_bf16 v[114:117], v[152:155], v[192:195], v[114:117]
	v_mfma_f32_16x16x32_bf16 v[110:113], v[144:147], v[200:203], v[110:113]
	v_mfma_f32_16x16x32_bf16 v[106:109], v[152:155], v[200:203], v[106:109]
	v_mfma_f32_16x16x32_bf16 v[102:105], v[144:147], v[208:211], v[102:105]
	v_mfma_f32_16x16x32_bf16 v[98:101], v[152:155], v[208:211], v[98:101]
	s_setprio 0
	s_setprio 1
	v_mfma_f32_16x16x32_bf16 v[94:97], v[156:159], v[180:183], v[94:97]
	v_mfma_f32_16x16x32_bf16 v[90:93], v[164:167], v[180:183], v[90:93]
	v_mfma_f32_16x16x32_bf16 v[86:89], v[156:159], v[188:191], v[86:89]
	v_mfma_f32_16x16x32_bf16 v[82:85], v[164:167], v[188:191], v[82:85]
	v_mfma_f32_16x16x32_bf16 v[78:81], v[156:159], v[196:199], v[78:81]
	v_mfma_f32_16x16x32_bf16 v[74:77], v[164:167], v[196:199], v[74:77]
	v_mfma_f32_16x16x32_bf16 v[70:73], v[156:159], v[204:207], v[70:73]
	v_mfma_f32_16x16x32_bf16 v[66:69], v[164:167], v[204:207], v[66:69]
	v_mfma_f32_16x16x32_bf16 v[94:97], v[160:163], v[184:187], v[94:97]
	v_mfma_f32_16x16x32_bf16 v[90:93], v[176:179], v[184:187], v[90:93]
	v_mfma_f32_16x16x32_bf16 v[86:89], v[160:163], v[192:195], v[86:89]
	v_mfma_f32_16x16x32_bf16 v[82:85], v[176:179], v[192:195], v[82:85]
	v_mfma_f32_16x16x32_bf16 v[78:81], v[160:163], v[200:203], v[78:81]
	v_mfma_f32_16x16x32_bf16 v[74:77], v[176:179], v[200:203], v[74:77]
	v_mfma_f32_16x16x32_bf16 v[70:73], v[160:163], v[208:211], v[70:73]
	v_mfma_f32_16x16x32_bf16 v[66:69], v[176:179], v[208:211], v[66:69]
	s_barrier
	s_setprio 0
	s_add_i32 s8, s83, s53
	v_lshl_add_u64 v[212:213], s[10:11], 0, v[0:1]
	s_mov_b32 m0, s8
	ds_read_b128 v[180:183], v245 offset:16384
	ds_read_b128 v[184:187], v245 offset:17408
	ds_read_b128 v[188:191], v245 offset:18432
	ds_read_b128 v[192:195], v245 offset:19456
	ds_read_b128 v[196:199], v245 offset:20480
	ds_read_b128 v[200:203], v245 offset:21504
	ds_read_b128 v[204:207], v245 offset:22528
	ds_read_b128 v[208:211], v245 offset:23552
	global_load_lds_dwordx4 v[212:213], off
	s_add_i32 m0, s8, 0x2000
	s_add_u32 s8, s10, 0x20000
	v_lshl_add_u64 v[214:215], s[10:11], 0, v[130:131]
	s_addc_u32 s9, s11, 0
	s_add_i32 s83, s91, s53
	global_load_lds_dwordx4 v[214:215], off
	v_lshl_add_u64 v[216:217], s[8:9], 0, v[0:1]
	s_mov_b32 m0, s83
	v_lshl_add_u64 v[218:219], s[44:45], 0, v[132:133]
	global_load_lds_dwordx4 v[216:217], off
	v_lshl_add_u64 v[216:217], s[8:9], 0, v[130:131]
	s_add_i32 m0, s83, 0x2000
	s_nop 0
	global_load_lds_dwordx4 v[216:217], off
	v_lshl_add_u64 v[216:217], s[44:45], 0, v[134:135]
	s_mov_b32 m0, s54
	s_nop 0
	global_load_lds_dwordx4 v[216:217], off
	s_mov_b32 m0, s55
	s_nop 0
	global_load_lds_dwordx4 v[218:219], off
	s_cmp_lg_u32 s101, 0
	s_cbranch_scc1 .Lskw_2_2
	s_waitcnt vmcnt(8)
.Lskw_2_2:
	s_mov_b32 s101, 0
	s_waitcnt lgkmcnt(0)
	s_barrier
	s_setprio 1
	v_mfma_f32_16x16x32_bf16 v[62:65], v[140:143], v[180:183], v[62:65]
	v_mfma_f32_16x16x32_bf16 v[58:61], v[148:151], v[180:183], v[58:61]
	v_mfma_f32_16x16x32_bf16 v[54:57], v[140:143], v[188:191], v[54:57]
	v_mfma_f32_16x16x32_bf16 v[50:53], v[148:151], v[188:191], v[50:53]
	v_mfma_f32_16x16x32_bf16 v[46:49], v[140:143], v[196:199], v[46:49]
	v_mfma_f32_16x16x32_bf16 v[42:45], v[148:151], v[196:199], v[42:45]
	v_mfma_f32_16x16x32_bf16 v[38:41], v[140:143], v[204:207], v[38:41]
	v_mfma_f32_16x16x32_bf16 v[34:37], v[148:151], v[204:207], v[34:37]
	v_mfma_f32_16x16x32_bf16 v[62:65], v[144:147], v[184:187], v[62:65]
	v_mfma_f32_16x16x32_bf16 v[58:61], v[152:155], v[184:187], v[58:61]
	v_mfma_f32_16x16x32_bf16 v[54:57], v[144:147], v[192:195], v[54:57]
	v_mfma_f32_16x16x32_bf16 v[50:53], v[152:155], v[192:195], v[50:53]
	v_mfma_f32_16x16x32_bf16 v[46:49], v[144:147], v[200:203], v[46:49]
	v_mfma_f32_16x16x32_bf16 v[42:45], v[152:155], v[200:203], v[42:45]
	v_mfma_f32_16x16x32_bf16 v[38:41], v[144:147], v[208:211], v[38:41]
	v_mfma_f32_16x16x32_bf16 v[34:37], v[152:155], v[208:211], v[34:37]
	s_setprio 0
	s_setprio 1
	v_mfma_f32_16x16x32_bf16 v[30:33], v[156:159], v[180:183], v[30:33]
	v_mfma_f32_16x16x32_bf16 v[26:29], v[164:167], v[180:183], v[26:29]
	v_mfma_f32_16x16x32_bf16 v[22:25], v[156:159], v[188:191], v[22:25]
	v_mfma_f32_16x16x32_bf16 v[18:21], v[164:167], v[188:191], v[18:21]
	v_mfma_f32_16x16x32_bf16 v[14:17], v[156:159], v[196:199], v[14:17]
	v_mfma_f32_16x16x32_bf16 v[10:13], v[164:167], v[196:199], v[10:13]
	v_mfma_f32_16x16x32_bf16 v[6:9], v[156:159], v[204:207], v[6:9]
	v_mfma_f32_16x16x32_bf16 v[2:5], v[164:167], v[204:207], v[2:5]
	v_mfma_f32_16x16x32_bf16 v[30:33], v[160:163], v[184:187], v[30:33]
	v_mfma_f32_16x16x32_bf16 v[26:29], v[176:179], v[184:187], v[26:29]
	v_mfma_f32_16x16x32_bf16 v[22:25], v[160:163], v[192:195], v[22:25]
	v_mfma_f32_16x16x32_bf16 v[18:21], v[176:179], v[192:195], v[18:21]
	v_mfma_f32_16x16x32_bf16 v[14:17], v[160:163], v[200:203], v[14:17]
	v_mfma_f32_16x16x32_bf16 v[10:13], v[176:179], v[200:203], v[10:13]
	v_mfma_f32_16x16x32_bf16 v[6:9], v[160:163], v[208:211], v[6:9]
	v_mfma_f32_16x16x32_bf16 v[2:5], v[176:179], v[208:211], v[2:5]
	s_barrier
; #define PG8_STAGE(bufoff, gbase, voff) do { _Pragma("unroll") for (int _i = 0; _i < 2; ++_i) \
;         __builtin_amdgcn_global_load_lds((const unsigned*)((const char*)(gbase) + (voff)[_i]), (LAS unsigned*)(lds + (bufoff) + ldsw + _i * 8192), 16, 0, 0); } while (0)
; #define PG8_LDA(dst, b, h) do { _Pragma("unroll") for (int m = 0; m < 4; ++m) _Pragma("unroll") for (int k = 0; k < 2; ++k) dst[m][k] = *(const LAS bf16x8*)(lds + PG8_SA(b, h) + aoff + m * 2048 + k * 1024); } while (0)
; #define PG8_LDB(dst, b, h) do { _Pragma("unroll") for (int n = 0; n < 2; ++n) _Pragma("unroll") for (int k = 0; k < 2; ++k) dst[n][k] = *(const LAS bf16x8*)(lds + PG8_SB(b, h) + boff + n * 2048 + k * 1024); } while (0)
; #define PG8_MMA(ai, bj, At, Bt) do { __builtin_amdgcn_s_setprio(1); _Pragma("unroll") for (int m = 0; m < 4; ++m) _Pragma("unroll") for (int n = 0; n < 2; ++n) _Pragma("unroll") for (int k = 0; k < 2; ++k) \
;         acc[ai][bj][m][n] = __builtin_amdgcn_mfma_f32_16x16x32_bf16(Bt[n][k], At[m][k], acc[ai][bj][m][n], 0, 0, 0); __builtin_amdgcn_s_setprio(0); } while (0)
; #define PG8_WAIT_V(n) asm volatile("s_waitcnt vmcnt(" #n ")" ::: "memory")
; #define PG8_WAIT_L(n) asm volatile("s_waitcnt lgkmcnt(" #n ")" ::: "memory")
; #define PG8_BAR __builtin_amdgcn_s_barrier()
; #define PG8_SCHED __builtin_amdgcn_sched_barrier(0)
; template <class Epi, class Sched, int NSEG, int KK, int LDA, int LDB>
; __device__ __forceinline__ void gemm_phase(LAS unsigned char* lds, const Gemm g, const Sched& S, const Epi& E) {
;     ...
;             PG8_LDB(B0, 1, 0); PG8_LDB(B1, 1, 1); PG8_SCHED; PG8_LDA(At, 1, 0); PG8_STAGE(PG8_SA(0, 1), a2 + hstepA, voffA);
;             PG8_WAIT_V(8); PG8_WAIT_L(0); PG8_BAR; PG8_MMA(0, 0, At, B0); PG8_MMA(0, 1, At, B1); PG8_BAR; PG8_SCHED;
	s_setprio 0
	s_add_i32 s83, 0, 0x18000
	s_add_i32 s91, 0, 0x1c000
	v_add_u32_e32 v152, s83, v244
	v_add_u32_e32 v172, s91, v244
	ds_read_b128 v[140:143], v152
	ds_read_b128 v[144:147], v152 offset:1024
	ds_read_b128 v[148:151], v152 offset:2048
	ds_read_b128 v[152:155], v152 offset:3072
	ds_read_b128 v[156:159], v172
	ds_read_b128 v[160:163], v172 offset:1024
	ds_read_b128 v[164:167], v172 offset:2048
	ds_read_b128 v[176:179], v172 offset:3072
	s_add_u32 s8, s44, 0x120000
	s_addc_u32 s9, s45, 0
	s_mov_b32 m0, s56
	v_lshl_add_u64 v[220:221], s[8:9], 0, v[134:135]
	ds_read_b128 v[180:183], v245 offset:32768
	ds_read_b128 v[184:187], v245 offset:33792
	ds_read_b128 v[188:191], v245 offset:34816
	ds_read_b128 v[192:195], v245 offset:35840
	ds_read_b128 v[196:199], v245 offset:36864
	ds_read_b128 v[200:203], v245 offset:37888
	ds_read_b128 v[204:207], v245 offset:38912
	ds_read_b128 v[208:211], v245 offset:39936
	global_load_lds_dwordx4 v[220:221], off
	v_lshl_add_u64 v[220:221], s[8:9], 0, v[132:133]
	s_mov_b32 m0, s57
	s_nop 0
	global_load_lds_dwordx4 v[220:221], off
	s_waitcnt vmcnt(8)
	s_waitcnt lgkmcnt(0)
	s_barrier
	s_setprio 1
	v_mfma_f32_16x16x32_bf16 v[126:129], v[140:143], v[180:183], v[126:129]
	v_mfma_f32_16x16x32_bf16 v[122:125], v[148:151], v[180:183], v[122:125]
	v_mfma_f32_16x16x32_bf16 v[118:121], v[140:143], v[188:191], v[118:121]
	v_mfma_f32_16x16x32_bf16 v[114:117], v[148:151], v[188:191], v[114:117]
	v_mfma_f32_16x16x32_bf16 v[110:113], v[140:143], v[196:199], v[110:113]
	v_mfma_f32_16x16x32_bf16 v[106:109], v[148:151], v[196:199], v[106:109]
	v_mfma_f32_16x16x32_bf16 v[102:105], v[140:143], v[204:207], v[102:105]
	v_mfma_f32_16x16x32_bf16 v[98:101], v[148:151], v[204:207], v[98:101]
	v_mfma_f32_16x16x32_bf16 v[126:129], v[144:147], v[184:187], v[126:129]
	v_mfma_f32_16x16x32_bf16 v[122:125], v[152:155], v[184:187], v[122:125]
	v_mfma_f32_16x16x32_bf16 v[118:121], v[144:147], v[192:195], v[118:121]
	v_mfma_f32_16x16x32_bf16 v[114:117], v[152:155], v[192:195], v[114:117]
	v_mfma_f32_16x16x32_bf16 v[110:113], v[144:147], v[200:203], v[110:113]
	v_mfma_f32_16x16x32_bf16 v[106:109], v[152:155], v[200:203], v[106:109]
	v_mfma_f32_16x16x32_bf16 v[102:105], v[144:147], v[208:211], v[102:105]
	v_mfma_f32_16x16x32_bf16 v[98:101], v[152:155], v[208:211], v[98:101]
	s_setprio 0
	s_setprio 1
	v_mfma_f32_16x16x32_bf16 v[94:97], v[156:159], v[180:183], v[94:97]
	v_mfma_f32_16x16x32_bf16 v[90:93], v[164:167], v[180:183], v[90:93]
	v_mfma_f32_16x16x32_bf16 v[86:89], v[156:159], v[188:191], v[86:89]
	v_mfma_f32_16x16x32_bf16 v[82:85], v[164:167], v[188:191], v[82:85]
	v_mfma_f32_16x16x32_bf16 v[78:81], v[156:159], v[196:199], v[78:81]
	v_mfma_f32_16x16x32_bf16 v[74:77], v[164:167], v[196:199], v[74:77]
	v_mfma_f32_16x16x32_bf16 v[70:73], v[156:159], v[204:207], v[70:73]
	v_mfma_f32_16x16x32_bf16 v[66:69], v[164:167], v[204:207], v[66:69]
	v_mfma_f32_16x16x32_bf16 v[94:97], v[160:163], v[184:187], v[94:97]
	v_mfma_f32_16x16x32_bf16 v[90:93], v[176:179], v[184:187], v[90:93]
	v_mfma_f32_16x16x32_bf16 v[86:89], v[160:163], v[192:195], v[86:89]
	v_mfma_f32_16x16x32_bf16 v[82:85], v[176:179], v[192:195], v[82:85]
	v_mfma_f32_16x16x32_bf16 v[78:81], v[160:163], v[200:203], v[78:81]
	v_mfma_f32_16x16x32_bf16 v[74:77], v[176:179], v[200:203], v[74:77]
	v_mfma_f32_16x16x32_bf16 v[70:73], v[160:163], v[208:211], v[70:73]
	v_mfma_f32_16x16x32_bf16 v[66:69], v[176:179], v[208:211], v[66:69]
	s_barrier
; #define PG8_STAGE(bufoff, gbase, voff) do { _Pragma("unroll") for (int _i = 0; _i < 2; ++_i) \
;         __builtin_amdgcn_global_load_lds((const unsigned*)((const char*)(gbase) + (voff)[_i]), (LAS unsigned*)(lds + (bufoff) + ldsw + _i * 8192), 16, 0, 0); } while (0)
; #define PG8_LDA(dst, b, h) do { _Pragma("unroll") for (int m = 0; m < 4; ++m) _Pragma("unroll") for (int k = 0; k < 2; ++k) dst[m][k] = *(const LAS bf16x8*)(lds + PG8_SA(b, h) + aoff + m * 2048 + k * 1024); } while (0)
; #define PG8_MMA(ai, bj, At, Bt) do { __builtin_amdgcn_s_setprio(1); _Pragma("unroll") for (int m = 0; m < 4; ++m) _Pragma("unroll") for (int n = 0; n < 2; ++n) _Pragma("unroll") for (int k = 0; k < 2; ++k) \
;         acc[ai][bj][m][n] = __builtin_amdgcn_mfma_f32_16x16x32_bf16(Bt[n][k], At[m][k], acc[ai][bj][m][n], 0, 0, 0); __builtin_amdgcn_s_setprio(0); } while (0)
; #define PG8_WAIT_V(n) asm volatile("s_waitcnt vmcnt(" #n ")" ::: "memory")
; #define PG8_WAIT_L(n) asm volatile("s_waitcnt lgkmcnt(" #n ")" ::: "memory")
; #define PG8_BAR __builtin_amdgcn_s_barrier()
; #define PG8_SCHED __builtin_amdgcn_sched_barrier(0)
; template <class Epi, class Sched, int NSEG, int KK, int LDA, int LDB>
; __device__ __forceinline__ void gemm_phase(LAS unsigned char* lds, const Gemm g, const Sched& S, const Epi& E) {
;     ...
;             PG8_LDA(At, 1, 1); PG8_STAGE(PG8_SB(1, 0), b3, voffB); PG8_STAGE(PG8_SB(1, 1), b3 + hstepB, voffB); PG8_STAGE(PG8_SA(1, 0), a3, voffA);
;             PG8_WAIT_V(8); PG8_WAIT_L(0); PG8_BAR; PG8_MMA(1, 0, At, B0); PG8_MMA(1, 1, At, B1); PG8_BAR; PG8_SCHED;
;         }
;         if (wr == 0) PG8_BAR;
	s_setprio 0
	s_add_i32 s8, s83, s53
	v_lshl_add_u64 v[212:213], v[212:213], 0, s[28:29]
	s_mov_b32 m0, s8
	ds_read_b128 v[180:183], v245 offset:49152
	ds_read_b128 v[184:187], v245 offset:50176
	ds_read_b128 v[188:191], v245 offset:51200
	ds_read_b128 v[192:195], v245 offset:52224
	ds_read_b128 v[196:199], v245 offset:53248
	ds_read_b128 v[200:203], v245 offset:54272
	ds_read_b128 v[204:207], v245 offset:55296
	ds_read_b128 v[208:211], v245 offset:56320
	global_load_lds_dwordx4 v[212:213], off
	s_add_i32 m0, s8, 0x2000
	s_add_u32 s8, s10, 0x20080
	v_lshl_add_u64 v[212:213], v[214:215], 0, s[28:29]
	s_addc_u32 s9, s11, 0
	s_add_i32 s10, s91, s53
	global_load_lds_dwordx4 v[212:213], off
	v_lshl_add_u64 v[212:213], s[8:9], 0, v[0:1]
	s_mov_b32 m0, s10
	s_nop 0
	global_load_lds_dwordx4 v[212:213], off
	v_lshl_add_u64 v[212:213], s[8:9], 0, v[130:131]
	s_add_i32 m0, s10, 0x2000
	s_nop 0
	global_load_lds_dwordx4 v[212:213], off
	v_lshl_add_u64 v[212:213], v[216:217], 0, s[28:29]
	s_mov_b32 m0, s59
	s_nop 0
	global_load_lds_dwordx4 v[212:213], off
	v_lshl_add_u64 v[212:213], v[218:219], 0, s[28:29]
	s_mov_b32 m0, s60
	s_nop 0
	global_load_lds_dwordx4 v[212:213], off
	s_waitcnt vmcnt(8)
	s_waitcnt lgkmcnt(0)
	s_barrier
	s_setprio 1
	v_mfma_f32_16x16x32_bf16 v[62:65], v[140:143], v[180:183], v[62:65]
	v_mfma_f32_16x16x32_bf16 v[58:61], v[148:151], v[180:183], v[58:61]
	v_mfma_f32_16x16x32_bf16 v[54:57], v[140:143], v[188:191], v[54:57]
	v_mfma_f32_16x16x32_bf16 v[50:53], v[148:151], v[188:191], v[50:53]
	v_mfma_f32_16x16x32_bf16 v[46:49], v[140:143], v[196:199], v[46:49]
	v_mfma_f32_16x16x32_bf16 v[42:45], v[148:151], v[196:199], v[42:45]
	v_mfma_f32_16x16x32_bf16 v[38:41], v[140:143], v[204:207], v[38:41]
	v_mfma_f32_16x16x32_bf16 v[34:37], v[148:151], v[204:207], v[34:37]
	v_mfma_f32_16x16x32_bf16 v[62:65], v[144:147], v[184:187], v[62:65]
	v_mfma_f32_16x16x32_bf16 v[58:61], v[152:155], v[184:187], v[58:61]
	v_mfma_f32_16x16x32_bf16 v[54:57], v[144:147], v[192:195], v[54:57]
	v_mfma_f32_16x16x32_bf16 v[50:53], v[152:155], v[192:195], v[50:53]
	v_mfma_f32_16x16x32_bf16 v[46:49], v[144:147], v[200:203], v[46:49]
	v_mfma_f32_16x16x32_bf16 v[42:45], v[152:155], v[200:203], v[42:45]
	v_mfma_f32_16x16x32_bf16 v[38:41], v[144:147], v[208:211], v[38:41]
	v_mfma_f32_16x16x32_bf16 v[34:37], v[152:155], v[208:211], v[34:37]
	s_setprio 0
	s_setprio 1
	v_mfma_f32_16x16x32_bf16 v[30:33], v[156:159], v[180:183], v[30:33]
	v_mfma_f32_16x16x32_bf16 v[26:29], v[164:167], v[180:183], v[26:29]
	v_mfma_f32_16x16x32_bf16 v[22:25], v[156:159], v[188:191], v[22:25]
	v_mfma_f32_16x16x32_bf16 v[18:21], v[164:167], v[188:191], v[18:21]
	v_mfma_f32_16x16x32_bf16 v[14:17], v[156:159], v[196:199], v[14:17]
	v_mfma_f32_16x16x32_bf16 v[10:13], v[164:167], v[196:199], v[10:13]
	v_mfma_f32_16x16x32_bf16 v[6:9], v[156:159], v[204:207], v[6:9]
	v_mfma_f32_16x16x32_bf16 v[2:5], v[164:167], v[204:207], v[2:5]
	v_mfma_f32_16x16x32_bf16 v[30:33], v[160:163], v[184:187], v[30:33]
	v_mfma_f32_16x16x32_bf16 v[26:29], v[176:179], v[184:187], v[26:29]
	v_mfma_f32_16x16x32_bf16 v[22:25], v[160:163], v[192:195], v[22:25]
	v_mfma_f32_16x16x32_bf16 v[18:21], v[176:179], v[192:195], v[18:21]
	v_mfma_f32_16x16x32_bf16 v[14:17], v[160:163], v[200:203], v[14:17]
	v_mfma_f32_16x16x32_bf16 v[10:13], v[176:179], v[200:203], v[10:13]
	v_mfma_f32_16x16x32_bf16 v[6:9], v[160:163], v[208:211], v[6:9]
	v_mfma_f32_16x16x32_bf16 v[2:5], v[176:179], v[208:211], v[2:5]
	s_barrier
	s_setprio 0
	s_add_i32 s77, s77, 2
	s_add_u32 s49, s49, 0x100
	s_addc_u32 s63, s63, 0
	s_cmp_gt_u32 s77, 5
	s_mov_b64 s[8:9], s[42:43]
	s_cbranch_scc0 .LBB0_759
	s_mov_b32 s101, 1
	s_and_b64 vcc, exec, s[46:47]
	s_cbranch_vccz .LBB0_762
	s_barrier

; #define PG8_STAGE(bufoff, gbase, voff) do { _Pragma("unroll") for (int _i = 0; _i < 2; ++_i) \
;         __builtin_amdgcn_global_load_lds((const unsigned*)((const char*)(gbase) + (voff)[_i]), (LAS unsigned*)(lds + (bufoff) + ldsw + _i * 8192), 16, 0, 0); } while (0)
; #define PG8_LDA(dst, b, h) do { _Pragma("unroll") for (int m = 0; m < 4; ++m) _Pragma("unroll") for (int k = 0; k < 2; ++k) dst[m][k] = *(const LAS bf16x8*)(lds + PG8_SA(b, h) + aoff + m * 2048 + k * 1024); } while (0)
; #define PG8_MMA(ai, bj, At, Bt) do { __builtin_amdgcn_s_setprio(1); _Pragma("unroll") for (int m = 0; m < 4; ++m) _Pragma("unroll") for (int n = 0; n < 2; ++n) _Pragma("unroll") for (int k = 0; k < 2; ++k) \
;         acc[ai][bj][m][n] = __builtin_amdgcn_mfma_f32_16x16x32_bf16(Bt[n][k], At[m][k], acc[ai][bj][m][n], 0, 0, 0); __builtin_amdgcn_s_setprio(0); } while (0)
; #define PG8_WAIT_V(n) asm volatile("s_waitcnt vmcnt(" #n ")" ::: "memory")
; #define PG8_WAIT_L(n) asm volatile("s_waitcnt lgkmcnt(" #n ")" ::: "memory")
; #define PG8_BAR __builtin_amdgcn_s_barrier()
; #define PG8_SCHED __builtin_amdgcn_sched_barrier(0)
; template <class Epi, class Sched, int NSEG, int KK, int LDA, int LDB>
; __device__ __forceinline__ void gemm_phase(LAS unsigned char* lds, const Gemm g, const Sched& S, const Epi& E) {
;     ...
;             PG8_WAIT_V(8); PG8_WAIT_L(0); PG8_BAR; PG8_MMA(0, 0, At, B0); PG8_MMA(0, 1, At, B1); PG8_BAR; PG8_SCHED;
;             PG8_LDA(At, 0, 1); PG8_STAGE(PG8_SB(0, 0), b2, voffB); PG8_STAGE(PG8_SB(0, 1), b2 + hstepB, voffB); PG8_STAGE(PG8_SA(0, 0), a2, voffA);
;             PG8_WAIT_V(8); PG8_WAIT_L(0); PG8_BAR; PG8_MMA(1, 0, At, B0); PG8_MMA(1, 1, At, B1); PG8_BAR; PG8_SCHED;
.Lskw_3_1:
	s_waitcnt lgkmcnt(0)
	s_barrier
	s_setprio 1
	v_mfma_f32_16x16x32_bf16 v[126:129], v[136:139], v[180:183], v[126:129]
	v_mfma_f32_16x16x32_bf16 v[122:125], v[144:147], v[180:183], v[122:125]
	v_mfma_f32_16x16x32_bf16 v[110:113], v[136:139], v[188:191], v[110:113]
	v_mfma_f32_16x16x32_bf16 v[106:109], v[144:147], v[188:191], v[106:109]
	v_mfma_f32_16x16x32_bf16 v[94:97], v[136:139], v[196:199], v[94:97]
	v_mfma_f32_16x16x32_bf16 v[90:93], v[144:147], v[196:199], v[90:93]
	v_mfma_f32_16x16x32_bf16 v[78:81], v[136:139], v[204:207], v[78:81]
	v_mfma_f32_16x16x32_bf16 v[74:77], v[144:147], v[204:207], v[74:77]
	v_mfma_f32_16x16x32_bf16 v[126:129], v[140:143], v[184:187], v[126:129]
	v_mfma_f32_16x16x32_bf16 v[122:125], v[148:151], v[184:187], v[122:125]
	v_mfma_f32_16x16x32_bf16 v[110:113], v[140:143], v[192:195], v[110:113]
	v_mfma_f32_16x16x32_bf16 v[106:109], v[148:151], v[192:195], v[106:109]
	v_mfma_f32_16x16x32_bf16 v[94:97], v[140:143], v[200:203], v[94:97]
	v_mfma_f32_16x16x32_bf16 v[90:93], v[148:151], v[200:203], v[90:93]
	v_mfma_f32_16x16x32_bf16 v[78:81], v[140:143], v[208:211], v[78:81]
	v_mfma_f32_16x16x32_bf16 v[74:77], v[148:151], v[208:211], v[74:77]
	s_setprio 0
	s_setprio 1
	v_mfma_f32_16x16x32_bf16 v[118:121], v[152:155], v[180:183], v[118:121]
	v_mfma_f32_16x16x32_bf16 v[114:117], v[160:163], v[180:183], v[114:117]
	v_mfma_f32_16x16x32_bf16 v[102:105], v[152:155], v[188:191], v[102:105]
	v_mfma_f32_16x16x32_bf16 v[98:101], v[160:163], v[188:191], v[98:101]
	v_mfma_f32_16x16x32_bf16 v[86:89], v[152:155], v[196:199], v[86:89]
	v_mfma_f32_16x16x32_bf16 v[82:85], v[160:163], v[196:199], v[82:85]
	v_mfma_f32_16x16x32_bf16 v[70:73], v[152:155], v[204:207], v[70:73]
	v_mfma_f32_16x16x32_bf16 v[66:69], v[160:163], v[204:207], v[66:69]
	v_mfma_f32_16x16x32_bf16 v[118:121], v[156:159], v[184:187], v[118:121]
	v_mfma_f32_16x16x32_bf16 v[114:117], v[176:179], v[184:187], v[114:117]
	v_mfma_f32_16x16x32_bf16 v[102:105], v[156:159], v[192:195], v[102:105]
	v_mfma_f32_16x16x32_bf16 v[98:101], v[176:179], v[192:195], v[98:101]
	v_mfma_f32_16x16x32_bf16 v[86:89], v[156:159], v[200:203], v[86:89]
	v_mfma_f32_16x16x32_bf16 v[82:85], v[176:179], v[200:203], v[82:85]
	v_mfma_f32_16x16x32_bf16 v[70:73], v[156:159], v[208:211], v[70:73]
	v_mfma_f32_16x16x32_bf16 v[66:69], v[176:179], v[208:211], v[66:69]
	s_barrier
	s_setprio 0
	s_add_i32 s63, s63, s23
	v_lshl_add_u64 v[166:167], s[10:11], 0, v[0:1]
	s_mov_b32 m0, s63
	ds_read_b128 v[180:183], v165 offset:16384
	ds_read_b128 v[184:187], v165 offset:17408
	ds_read_b128 v[188:191], v165 offset:18432
	ds_read_b128 v[192:195], v165 offset:19456
	ds_read_b128 v[196:199], v165 offset:20480
	ds_read_b128 v[200:203], v165 offset:21504
	ds_read_b128 v[204:207], v165 offset:22528
	ds_read_b128 v[208:211], v165 offset:23552
	global_load_lds_dwordx4 v[166:167], off
	s_add_i32 m0, s63, 0x2000
	s_add_u32 s94, s10, 0x40000
	v_lshl_add_u64 v[172:173], s[10:11], 0, v[130:131]
	s_addc_u32 s95, s11, 0
	s_add_i32 s63, s77, s23
	global_load_lds_dwordx4 v[172:173], off
	v_lshl_add_u64 v[212:213], s[94:95], 0, v[0:1]
	s_mov_b32 m0, s63
	v_lshl_add_u64 v[214:215], s[44:45], 0, v[130:131]
	global_load_lds_dwordx4 v[212:213], off
	v_lshl_add_u64 v[212:213], s[94:95], 0, v[130:131]
	s_add_i32 m0, s63, 0x2000
	s_nop 0
	global_load_lds_dwordx4 v[212:213], off
	v_lshl_add_u64 v[212:213], s[44:45], 0, v[0:1]
	s_mov_b32 m0, s26
	s_nop 0
	global_load_lds_dwordx4 v[212:213], off
	s_mov_b32 m0, s33
	s_nop 0
	global_load_lds_dwordx4 v[214:215], off
	s_cmp_lg_u32 s101, 0
	s_cbranch_scc1 .Lskw_3_2
	s_waitcnt vmcnt(8)
.Lskw_3_2:
	s_mov_b32 s101, 0
	s_waitcnt lgkmcnt(0)
	s_barrier
	s_setprio 1
	v_mfma_f32_16x16x32_bf16 v[62:65], v[136:139], v[180:183], v[62:65]
	v_mfma_f32_16x16x32_bf16 v[58:61], v[144:147], v[180:183], v[58:61]
	v_mfma_f32_16x16x32_bf16 v[46:49], v[136:139], v[188:191], v[46:49]
	v_mfma_f32_16x16x32_bf16 v[42:45], v[144:147], v[188:191], v[42:45]
	v_mfma_f32_16x16x32_bf16 v[30:33], v[136:139], v[196:199], v[30:33]
	v_mfma_f32_16x16x32_bf16 v[26:29], v[144:147], v[196:199], v[26:29]
	v_mfma_f32_16x16x32_bf16 v[14:17], v[136:139], v[204:207], v[14:17]
	v_mfma_f32_16x16x32_bf16 v[10:13], v[144:147], v[204:207], v[10:13]
	v_mfma_f32_16x16x32_bf16 v[62:65], v[140:143], v[184:187], v[62:65]
	v_mfma_f32_16x16x32_bf16 v[58:61], v[148:151], v[184:187], v[58:61]
	v_mfma_f32_16x16x32_bf16 v[46:49], v[140:143], v[192:195], v[46:49]
	v_mfma_f32_16x16x32_bf16 v[42:45], v[148:151], v[192:195], v[42:45]
	v_mfma_f32_16x16x32_bf16 v[30:33], v[140:143], v[200:203], v[30:33]
	v_mfma_f32_16x16x32_bf16 v[26:29], v[148:151], v[200:203], v[26:29]
	v_mfma_f32_16x16x32_bf16 v[14:17], v[140:143], v[208:211], v[14:17]
	v_mfma_f32_16x16x32_bf16 v[10:13], v[148:151], v[208:211], v[10:13]
	s_setprio 0
	s_setprio 1
	v_mfma_f32_16x16x32_bf16 v[54:57], v[152:155], v[180:183], v[54:57]
	v_mfma_f32_16x16x32_bf16 v[50:53], v[160:163], v[180:183], v[50:53]
	v_mfma_f32_16x16x32_bf16 v[38:41], v[152:155], v[188:191], v[38:41]
	v_mfma_f32_16x16x32_bf16 v[34:37], v[160:163], v[188:191], v[34:37]
	v_mfma_f32_16x16x32_bf16 v[22:25], v[152:155], v[196:199], v[22:25]
	v_mfma_f32_16x16x32_bf16 v[18:21], v[160:163], v[196:199], v[18:21]
	v_mfma_f32_16x16x32_bf16 v[6:9], v[152:155], v[204:207], v[6:9]
	v_mfma_f32_16x16x32_bf16 v[2:5], v[160:163], v[204:207], v[2:5]
	v_mfma_f32_16x16x32_bf16 v[54:57], v[156:159], v[184:187], v[54:57]
	v_mfma_f32_16x16x32_bf16 v[50:53], v[176:179], v[184:187], v[50:53]
	v_mfma_f32_16x16x32_bf16 v[38:41], v[156:159], v[192:195], v[38:41]
	v_mfma_f32_16x16x32_bf16 v[34:37], v[176:179], v[192:195], v[34:37]
	v_mfma_f32_16x16x32_bf16 v[22:25], v[156:159], v[200:203], v[22:25]
	v_mfma_f32_16x16x32_bf16 v[18:21], v[176:179], v[200:203], v[18:21]
	v_mfma_f32_16x16x32_bf16 v[6:9], v[156:159], v[208:211], v[6:9]
	v_mfma_f32_16x16x32_bf16 v[2:5], v[176:179], v[208:211], v[2:5]
	s_barrier
; #define PG8_STAGE(bufoff, gbase, voff) do { _Pragma("unroll") for (int _i = 0; _i < 2; ++_i) \
;         __builtin_amdgcn_global_load_lds((const unsigned*)((const char*)(gbase) + (voff)[_i]), (LAS unsigned*)(lds + (bufoff) + ldsw + _i * 8192), 16, 0, 0); } while (0)
; #define PG8_LDA(dst, b, h) do { _Pragma("unroll") for (int m = 0; m < 4; ++m) _Pragma("unroll") for (int k = 0; k < 2; ++k) dst[m][k] = *(const LAS bf16x8*)(lds + PG8_SA(b, h) + aoff + m * 2048 + k * 1024); } while (0)
; #define PG8_LDB(dst, b, h) do { _Pragma("unroll") for (int n = 0; n < 2; ++n) _Pragma("unroll") for (int k = 0; k < 2; ++k) dst[n][k] = *(const LAS bf16x8*)(lds + PG8_SB(b, h) + boff + n * 2048 + k * 1024); } while (0)
; #define PG8_MMA(ai, bj, At, Bt) do { __builtin_amdgcn_s_setprio(1); _Pragma("unroll") for (int m = 0; m < 4; ++m) _Pragma("unroll") for (int n = 0; n < 2; ++n) _Pragma("unroll") for (int k = 0; k < 2; ++k) \
;         acc[ai][bj][m][n] = __builtin_amdgcn_mfma_f32_16x16x32_bf16(Bt[n][k], At[m][k], acc[ai][bj][m][n], 0, 0, 0); __builtin_amdgcn_s_setprio(0); } while (0)
; #define PG8_WAIT_V(n) asm volatile("s_waitcnt vmcnt(" #n ")" ::: "memory")
; #define PG8_WAIT_L(n) asm volatile("s_waitcnt lgkmcnt(" #n ")" ::: "memory")
; #define PG8_BAR __builtin_amdgcn_s_barrier()
; #define PG8_SCHED __builtin_amdgcn_sched_barrier(0)
; template <class Epi, class Sched, int NSEG, int KK, int LDA, int LDB>
; __device__ __forceinline__ void gemm_phase(LAS unsigned char* lds, const Gemm g, const Sched& S, const Epi& E) {
;     ...
;             PG8_LDB(B0, 1, 0); PG8_LDB(B1, 1, 1); PG8_SCHED; PG8_LDA(At, 1, 0); PG8_STAGE(PG8_SA(0, 1), a2 + hstepA, voffA);
;             PG8_WAIT_V(8); PG8_WAIT_L(0); PG8_BAR; PG8_MMA(0, 0, At, B0); PG8_MMA(0, 1, At, B1); PG8_BAR; PG8_SCHED;
	s_setprio 0
	s_add_i32 s63, 0, 0x18000
	s_add_i32 s77, 0, 0x1c000
	v_add_u32_e32 v148, s63, v164
	v_add_u32_e32 v176, s77, v164
	ds_read_b128 v[136:139], v148
	ds_read_b128 v[140:143], v148 offset:1024
	ds_read_b128 v[144:147], v148 offset:256
	ds_read_b128 v[148:151], v148 offset:1280
	ds_read_b128 v[152:155], v176
	ds_read_b128 v[156:159], v176 offset:1024
	ds_read_b128 v[160:163], v176 offset:256
	ds_read_b128 v[176:179], v176 offset:1280
	s_add_u32 s44, s44, 0x40000
	s_addc_u32 s45, s45, 0
	s_mov_b32 m0, s38
	v_lshl_add_u64 v[216:217], s[44:45], 0, v[0:1]
	ds_read_b128 v[180:183], v165 offset:32768
	ds_read_b128 v[184:187], v165 offset:33792
	ds_read_b128 v[188:191], v165 offset:34816
	ds_read_b128 v[192:195], v165 offset:35840
	ds_read_b128 v[196:199], v165 offset:36864
	ds_read_b128 v[200:203], v165 offset:37888
	ds_read_b128 v[204:207], v165 offset:38912
	ds_read_b128 v[208:211], v165 offset:39936
	global_load_lds_dwordx4 v[216:217], off
	v_lshl_add_u64 v[216:217], s[44:45], 0, v[130:131]
	s_mov_b32 m0, s39
	s_nop 0
	global_load_lds_dwordx4 v[216:217], off
	s_waitcnt vmcnt(8)
	s_waitcnt lgkmcnt(0)
	s_barrier
	s_setprio 1
	v_mfma_f32_16x16x32_bf16 v[126:129], v[136:139], v[180:183], v[126:129]
	v_mfma_f32_16x16x32_bf16 v[122:125], v[144:147], v[180:183], v[122:125]
	v_mfma_f32_16x16x32_bf16 v[110:113], v[136:139], v[188:191], v[110:113]
	v_mfma_f32_16x16x32_bf16 v[106:109], v[144:147], v[188:191], v[106:109]
	v_mfma_f32_16x16x32_bf16 v[94:97], v[136:139], v[196:199], v[94:97]
	v_mfma_f32_16x16x32_bf16 v[90:93], v[144:147], v[196:199], v[90:93]
	v_mfma_f32_16x16x32_bf16 v[78:81], v[136:139], v[204:207], v[78:81]
	v_mfma_f32_16x16x32_bf16 v[74:77], v[144:147], v[204:207], v[74:77]
	v_mfma_f32_16x16x32_bf16 v[126:129], v[140:143], v[184:187], v[126:129]
	v_mfma_f32_16x16x32_bf16 v[122:125], v[148:151], v[184:187], v[122:125]
	v_mfma_f32_16x16x32_bf16 v[110:113], v[140:143], v[192:195], v[110:113]
	v_mfma_f32_16x16x32_bf16 v[106:109], v[148:151], v[192:195], v[106:109]
	v_mfma_f32_16x16x32_bf16 v[94:97], v[140:143], v[200:203], v[94:97]
	v_mfma_f32_16x16x32_bf16 v[90:93], v[148:151], v[200:203], v[90:93]
	v_mfma_f32_16x16x32_bf16 v[78:81], v[140:143], v[208:211], v[78:81]
	v_mfma_f32_16x16x32_bf16 v[74:77], v[148:151], v[208:211], v[74:77]
	s_setprio 0
	s_setprio 1
	v_mfma_f32_16x16x32_bf16 v[118:121], v[152:155], v[180:183], v[118:121]
	v_mfma_f32_16x16x32_bf16 v[114:117], v[160:163], v[180:183], v[114:117]
	v_mfma_f32_16x16x32_bf16 v[102:105], v[152:155], v[188:191], v[102:105]
	v_mfma_f32_16x16x32_bf16 v[98:101], v[160:163], v[188:191], v[98:101]
	v_mfma_f32_16x16x32_bf16 v[86:89], v[152:155], v[196:199], v[86:89]
	v_mfma_f32_16x16x32_bf16 v[82:85], v[160:163], v[196:199], v[82:85]
	v_mfma_f32_16x16x32_bf16 v[70:73], v[152:155], v[204:207], v[70:73]
	v_mfma_f32_16x16x32_bf16 v[66:69], v[160:163], v[204:207], v[66:69]
	v_mfma_f32_16x16x32_bf16 v[118:121], v[156:159], v[184:187], v[118:121]
	v_mfma_f32_16x16x32_bf16 v[114:117], v[176:179], v[184:187], v[114:117]
	v_mfma_f32_16x16x32_bf16 v[102:105], v[156:159], v[192:195], v[102:105]
	v_mfma_f32_16x16x32_bf16 v[98:101], v[176:179], v[192:195], v[98:101]
	v_mfma_f32_16x16x32_bf16 v[86:89], v[156:159], v[200:203], v[86:89]
	v_mfma_f32_16x16x32_bf16 v[82:85], v[176:179], v[200:203], v[82:85]
	v_mfma_f32_16x16x32_bf16 v[70:73], v[156:159], v[208:211], v[70:73]
	v_mfma_f32_16x16x32_bf16 v[66:69], v[176:179], v[208:211], v[66:69]
	s_barrier
; #define PG8_STAGE(bufoff, gbase, voff) do { _Pragma("unroll") for (int _i = 0; _i < 2; ++_i) \
;         __builtin_amdgcn_global_load_lds((const unsigned*)((const char*)(gbase) + (voff)[_i]), (LAS unsigned*)(lds + (bufoff) + ldsw + _i * 8192), 16, 0, 0); } while (0)
; #define PG8_LDA(dst, b, h) do { _Pragma("unroll") for (int m = 0; m < 4; ++m) _Pragma("unroll") for (int k = 0; k < 2; ++k) dst[m][k] = *(const LAS bf16x8*)(lds + PG8_SA(b, h) + aoff + m * 2048 + k * 1024); } while (0)
; #define PG8_MMA(ai, bj, At, Bt) do { __builtin_amdgcn_s_setprio(1); _Pragma("unroll") for (int m = 0; m < 4; ++m) _Pragma("unroll") for (int n = 0; n < 2; ++n) _Pragma("unroll") for (int k = 0; k < 2; ++k) \
;         acc[ai][bj][m][n] = __builtin_amdgcn_mfma_f32_16x16x32_bf16(Bt[n][k], At[m][k], acc[ai][bj][m][n], 0, 0, 0); __builtin_amdgcn_s_setprio(0); } while (0)
; #define PG8_WAIT_V(n) asm volatile("s_waitcnt vmcnt(" #n ")" ::: "memory")
; #define PG8_WAIT_L(n) asm volatile("s_waitcnt lgkmcnt(" #n ")" ::: "memory")
; #define PG8_BAR __builtin_amdgcn_s_barrier()
; #define PG8_SCHED __builtin_amdgcn_sched_barrier(0)
; template <class Epi, class Sched, int NSEG, int KK, int LDA, int LDB>
; __device__ __forceinline__ void gemm_phase(LAS unsigned char* lds, const Gemm g, const Sched& S, const Epi& E) {
;     ...
;             PG8_LDA(At, 1, 1); PG8_STAGE(PG8_SB(1, 0), b3, voffB); PG8_STAGE(PG8_SB(1, 1), b3 + hstepB, voffB); PG8_STAGE(PG8_SA(1, 0), a3, voffA);
;             PG8_WAIT_V(8); PG8_WAIT_L(0); PG8_BAR; PG8_MMA(1, 0, At, B0); PG8_MMA(1, 1, At, B1); PG8_BAR; PG8_SCHED;
;         }
;         if (wr == 0) PG8_BAR;
	s_setprio 0
	s_add_i32 s44, s63, s23
	v_lshl_add_u64 v[166:167], v[166:167], 0, s[28:29]
	s_mov_b32 m0, s44
	ds_read_b128 v[180:183], v165 offset:49152
	ds_read_b128 v[184:187], v165 offset:50176
	ds_read_b128 v[188:191], v165 offset:51200
	ds_read_b128 v[192:195], v165 offset:52224
	ds_read_b128 v[196:199], v165 offset:53248
	ds_read_b128 v[200:203], v165 offset:54272
	ds_read_b128 v[204:207], v165 offset:55296
	ds_read_b128 v[208:211], v165 offset:56320
	global_load_lds_dwordx4 v[166:167], off
	s_add_i32 m0, s44, 0x2000
	s_add_u32 s10, s10, 0x40080
	v_lshl_add_u64 v[166:167], v[172:173], 0, s[28:29]
	s_addc_u32 s11, s11, 0
	s_add_i32 s44, s77, s23
	global_load_lds_dwordx4 v[166:167], off
	v_lshl_add_u64 v[166:167], s[10:11], 0, v[0:1]
	s_mov_b32 m0, s44
	s_nop 0
	global_load_lds_dwordx4 v[166:167], off
	v_lshl_add_u64 v[166:167], s[10:11], 0, v[130:131]
	s_add_i32 m0, s44, 0x2000
	s_nop 0
	global_load_lds_dwordx4 v[166:167], off
	v_lshl_add_u64 v[166:167], v[212:213], 0, s[28:29]
	s_mov_b32 m0, s57
	s_nop 0
	global_load_lds_dwordx4 v[166:167], off
	v_lshl_add_u64 v[166:167], v[214:215], 0, s[28:29]
	s_mov_b32 m0, s58
	s_nop 0
	global_load_lds_dwordx4 v[166:167], off
	s_waitcnt vmcnt(8)
	s_waitcnt lgkmcnt(0)
	s_barrier
	s_setprio 1
	v_mfma_f32_16x16x32_bf16 v[62:65], v[136:139], v[180:183], v[62:65]
	v_mfma_f32_16x16x32_bf16 v[58:61], v[144:147], v[180:183], v[58:61]
	v_mfma_f32_16x16x32_bf16 v[46:49], v[136:139], v[188:191], v[46:49]
	v_mfma_f32_16x16x32_bf16 v[42:45], v[144:147], v[188:191], v[42:45]
	v_mfma_f32_16x16x32_bf16 v[30:33], v[136:139], v[196:199], v[30:33]
	v_mfma_f32_16x16x32_bf16 v[26:29], v[144:147], v[196:199], v[26:29]
	v_mfma_f32_16x16x32_bf16 v[14:17], v[136:139], v[204:207], v[14:17]
	v_mfma_f32_16x16x32_bf16 v[10:13], v[144:147], v[204:207], v[10:13]
	v_mfma_f32_16x16x32_bf16 v[62:65], v[140:143], v[184:187], v[62:65]
	v_mfma_f32_16x16x32_bf16 v[58:61], v[148:151], v[184:187], v[58:61]
	v_mfma_f32_16x16x32_bf16 v[46:49], v[140:143], v[192:195], v[46:49]
	v_mfma_f32_16x16x32_bf16 v[42:45], v[148:151], v[192:195], v[42:45]
	v_mfma_f32_16x16x32_bf16 v[30:33], v[140:143], v[200:203], v[30:33]
	v_mfma_f32_16x16x32_bf16 v[26:29], v[148:151], v[200:203], v[26:29]
	v_mfma_f32_16x16x32_bf16 v[14:17], v[140:143], v[208:211], v[14:17]
	v_mfma_f32_16x16x32_bf16 v[10:13], v[148:151], v[208:211], v[10:13]
	s_setprio 0
	s_setprio 1
	v_mfma_f32_16x16x32_bf16 v[54:57], v[152:155], v[180:183], v[54:57]
	v_mfma_f32_16x16x32_bf16 v[50:53], v[160:163], v[180:183], v[50:53]
	v_mfma_f32_16x16x32_bf16 v[38:41], v[152:155], v[188:191], v[38:41]
	v_mfma_f32_16x16x32_bf16 v[34:37], v[160:163], v[188:191], v[34:37]
	v_mfma_f32_16x16x32_bf16 v[22:25], v[152:155], v[196:199], v[22:25]
	v_mfma_f32_16x16x32_bf16 v[18:21], v[160:163], v[196:199], v[18:21]
	v_mfma_f32_16x16x32_bf16 v[6:9], v[152:155], v[204:207], v[6:9]
	v_mfma_f32_16x16x32_bf16 v[2:5], v[160:163], v[204:207], v[2:5]
	v_mfma_f32_16x16x32_bf16 v[54:57], v[156:159], v[184:187], v[54:57]
	v_mfma_f32_16x16x32_bf16 v[50:53], v[176:179], v[184:187], v[50:53]
	v_mfma_f32_16x16x32_bf16 v[38:41], v[156:159], v[192:195], v[38:41]
	v_mfma_f32_16x16x32_bf16 v[34:37], v[176:179], v[192:195], v[34:37]
	v_mfma_f32_16x16x32_bf16 v[22:25], v[156:159], v[200:203], v[22:25]
	v_mfma_f32_16x16x32_bf16 v[18:21], v[176:179], v[200:203], v[18:21]
	v_mfma_f32_16x16x32_bf16 v[6:9], v[156:159], v[208:211], v[6:9]
	v_mfma_f32_16x16x32_bf16 v[2:5], v[176:179], v[208:211], v[2:5]
	s_barrier
	s_setprio 0
	s_add_i32 s62, s62, 2
	s_add_u32 s42, s42, 0x100
	s_addc_u32 s43, s43, 0
	s_add_u32 s60, s60, 0x100
	s_addc_u32 s61, s61, 0
	s_cmp_gt_u32 s62, 13
	s_cbranch_scc0 .LBB0_985
	s_mov_b32 s101, 1
	s_and_b64 vcc, exec, s[8:9]
	s_cbranch_vccz .LBB0_988
	s_barrier

; #define PG8_STAGE(bufoff, gbase, voff) do { _Pragma("unroll") for (int _i = 0; _i < 2; ++_i) \
;         __builtin_amdgcn_global_load_lds((const unsigned*)((const char*)(gbase) + (voff)[_i]), (LAS unsigned*)(lds + (bufoff) + ldsw + _i * 8192), 16, 0, 0); } while (0)
; #define PG8_LDA(dst, b, h) do { _Pragma("unroll") for (int m = 0; m < 4; ++m) _Pragma("unroll") for (int k = 0; k < 2; ++k) dst[m][k] = *(const LAS bf16x8*)(lds + PG8_SA(b, h) + aoff + m * 2048 + k * 1024); } while (0)
; #define PG8_MMA(ai, bj, At, Bt) do { __builtin_amdgcn_s_setprio(1); _Pragma("unroll") for (int m = 0; m < 4; ++m) _Pragma("unroll") for (int n = 0; n < 2; ++n) _Pragma("unroll") for (int k = 0; k < 2; ++k) \
;         acc[ai][bj][m][n] = __builtin_amdgcn_mfma_f32_16x16x32_bf16(Bt[n][k], At[m][k], acc[ai][bj][m][n], 0, 0, 0); __builtin_amdgcn_s_setprio(0); } while (0)
; #define PG8_WAIT_V(n) asm volatile("s_waitcnt vmcnt(" #n ")" ::: "memory")
; #define PG8_WAIT_L(n) asm volatile("s_waitcnt lgkmcnt(" #n ")" ::: "memory")
; #define PG8_BAR __builtin_amdgcn_s_barrier()
; #define PG8_SCHED __builtin_amdgcn_sched_barrier(0)
; template <class Epi, class Sched, int NSEG, int KK, int LDA, int LDB>
; __device__ __forceinline__ void gemm_phase(LAS unsigned char* lds, const Gemm g, const Sched& S, const Epi& E) {
;     ...
;             PG8_WAIT_V(8); PG8_WAIT_L(0); PG8_BAR; PG8_MMA(0, 0, At, B0); PG8_MMA(0, 1, At, B1); PG8_BAR; PG8_SCHED;
;             PG8_LDA(At, 0, 1); PG8_STAGE(PG8_SB(0, 0), b2, voffB); PG8_STAGE(PG8_SB(0, 1), b2 + hstepB, voffB); PG8_STAGE(PG8_SA(0, 0), a2, voffA);
;             PG8_WAIT_V(8); PG8_WAIT_L(0); PG8_BAR; PG8_MMA(1, 0, At, B0); PG8_MMA(1, 1, At, B1); PG8_BAR; PG8_SCHED;
.Lskw_4_1:
	s_waitcnt lgkmcnt(0)
	s_barrier
	s_setprio 1
	v_mfma_f32_16x16x32_bf16 v[130:133], v[118:121], v[162:165], v[130:133]
	v_mfma_f32_16x16x32_bf16 v[126:129], v[138:141], v[162:165], v[126:129]
	v_mfma_f32_16x16x32_bf16 v[110:113], v[118:121], v[192:195], v[110:113]
	v_mfma_f32_16x16x32_bf16 v[46:49], v[138:141], v[192:195], v[46:49]
	v_mfma_f32_16x16x32_bf16 v[106:109], v[118:121], v[200:203], v[106:109]
	v_mfma_f32_16x16x32_bf16 v[42:45], v[138:141], v[200:203], v[42:45]
	v_mfma_f32_16x16x32_bf16 v[114:117], v[118:121], v[208:211], v[114:117]
	v_mfma_f32_16x16x32_bf16 v[50:53], v[138:141], v[208:211], v[50:53]
	v_mfma_f32_16x16x32_bf16 v[130:133], v[134:137], v[188:191], v[130:133]
	v_mfma_f32_16x16x32_bf16 v[126:129], v[142:145], v[188:191], v[126:129]
	v_mfma_f32_16x16x32_bf16 v[110:113], v[134:137], v[196:199], v[110:113]
	v_mfma_f32_16x16x32_bf16 v[46:49], v[142:145], v[196:199], v[46:49]
	v_mfma_f32_16x16x32_bf16 v[106:109], v[134:137], v[204:207], v[106:109]
	v_mfma_f32_16x16x32_bf16 v[42:45], v[142:145], v[204:207], v[42:45]
	v_mfma_f32_16x16x32_bf16 v[114:117], v[134:137], v[212:215], v[114:117]
	v_mfma_f32_16x16x32_bf16 v[50:53], v[142:145], v[212:215], v[50:53]
	s_setprio 0
	s_setprio 1
	v_mfma_f32_16x16x32_bf16 v[122:125], v[146:149], v[162:165], v[122:125]
	v_mfma_f32_16x16x32_bf16 v[62:65], v[154:157], v[162:165], v[62:65]
	v_mfma_f32_16x16x32_bf16 v[102:105], v[146:149], v[192:195], v[102:105]
	v_mfma_f32_16x16x32_bf16 v[38:41], v[154:157], v[192:195], v[38:41]
	v_mfma_f32_16x16x32_bf16 v[98:101], v[146:149], v[200:203], v[98:101]
	v_mfma_f32_16x16x32_bf16 v[34:37], v[154:157], v[200:203], v[34:37]
	v_mfma_f32_16x16x32_bf16 v[90:93], v[146:149], v[208:211], v[90:93]
	v_mfma_f32_16x16x32_bf16 v[54:57], v[154:157], v[208:211], v[54:57]
	v_mfma_f32_16x16x32_bf16 v[122:125], v[150:153], v[188:191], v[122:125]
	v_mfma_f32_16x16x32_bf16 v[62:65], v[158:161], v[188:191], v[62:65]
	v_mfma_f32_16x16x32_bf16 v[102:105], v[150:153], v[196:199], v[102:105]
	v_mfma_f32_16x16x32_bf16 v[38:41], v[158:161], v[196:199], v[38:41]
	v_mfma_f32_16x16x32_bf16 v[98:101], v[150:153], v[204:207], v[98:101]
	v_mfma_f32_16x16x32_bf16 v[34:37], v[158:161], v[204:207], v[34:37]
	v_mfma_f32_16x16x32_bf16 v[90:93], v[150:153], v[212:215], v[90:93]
	v_mfma_f32_16x16x32_bf16 v[54:57], v[158:161], v[212:215], v[54:57]
	s_barrier
	s_setprio 0
	s_add_i32 s55, s55, s38
	v_lshl_add_u64 v[172:173], s[10:11], 0, v[180:181]
	s_mov_b32 m0, s55
	ds_read_b128 v[162:165], v166 offset:16384
	ds_read_b128 v[188:191], v166 offset:17408
	ds_read_b128 v[192:195], v166 offset:18432
	ds_read_b128 v[196:199], v166 offset:19456
	ds_read_b128 v[200:203], v166 offset:20480
	ds_read_b128 v[204:207], v166 offset:21504
	ds_read_b128 v[208:211], v166 offset:22528
	ds_read_b128 v[212:215], v166 offset:23552
	global_load_lds_dwordx4 v[172:173], off
	s_add_i32 m0, s55, 0x2000
	s_add_u32 s60, s10, 0x40000
	v_lshl_add_u64 v[216:217], s[10:11], 0, v[176:177]
	s_addc_u32 s61, s11, 0
	s_add_i32 s55, s62, s38
	global_load_lds_dwordx4 v[216:217], off
	v_lshl_add_u64 v[218:219], s[60:61], 0, v[180:181]
	s_mov_b32 m0, s55
	v_lshl_add_u64 v[220:221], s[44:45], 0, v[178:179]
	global_load_lds_dwordx4 v[218:219], off
	v_lshl_add_u64 v[218:219], s[60:61], 0, v[176:177]
	s_add_i32 m0, s55, 0x2000
	s_nop 0
	global_load_lds_dwordx4 v[218:219], off
	v_lshl_add_u64 v[218:219], s[44:45], 0, v[182:183]
	s_mov_b32 m0, s39
	s_nop 0
	global_load_lds_dwordx4 v[218:219], off
	s_mov_b32 m0, s83
	s_nop 0
	global_load_lds_dwordx4 v[220:221], off
	s_cmp_lg_u32 s101, 0
	s_cbranch_scc1 .Lskw_4_2
	s_waitcnt vmcnt(8)
.Lskw_4_2:
	s_mov_b32 s101, 0
	s_waitcnt lgkmcnt(0)
	s_barrier
	s_setprio 1
	v_mfma_f32_16x16x32_bf16 v[94:97], v[118:121], v[162:165], v[94:97]
	v_mfma_f32_16x16x32_bf16 v[22:25], v[138:141], v[162:165], v[22:25]
	v_mfma_f32_16x16x32_bf16 v[86:89], v[118:121], v[192:195], v[86:89]
	v_mfma_f32_16x16x32_bf16 v[18:21], v[138:141], v[192:195], v[18:21]
	v_mfma_f32_16x16x32_bf16 v[74:77], v[118:121], v[200:203], v[74:77]
	v_mfma_f32_16x16x32_bf16 v[10:13], v[138:141], v[200:203], v[10:13]
	v_mfma_f32_16x16x32_bf16 v[82:85], v[118:121], v[208:211], v[82:85]
	v_mfma_f32_16x16x32_bf16 v[26:29], v[138:141], v[208:211], v[26:29]
	v_mfma_f32_16x16x32_bf16 v[94:97], v[134:137], v[188:191], v[94:97]
	v_mfma_f32_16x16x32_bf16 v[22:25], v[142:145], v[188:191], v[22:25]
	v_mfma_f32_16x16x32_bf16 v[86:89], v[134:137], v[196:199], v[86:89]
	v_mfma_f32_16x16x32_bf16 v[18:21], v[142:145], v[196:199], v[18:21]
	v_mfma_f32_16x16x32_bf16 v[74:77], v[134:137], v[204:207], v[74:77]
	v_mfma_f32_16x16x32_bf16 v[10:13], v[142:145], v[204:207], v[10:13]
	v_mfma_f32_16x16x32_bf16 v[82:85], v[134:137], v[212:215], v[82:85]
	v_mfma_f32_16x16x32_bf16 v[26:29], v[142:145], v[212:215], v[26:29]
	s_setprio 0
	s_setprio 1
	v_mfma_f32_16x16x32_bf16 v[78:81], v[146:149], v[162:165], v[78:81]
	v_mfma_f32_16x16x32_bf16 v[14:17], v[154:157], v[162:165], v[14:17]
	v_mfma_f32_16x16x32_bf16 v[70:73], v[146:149], v[192:195], v[70:73]
	v_mfma_f32_16x16x32_bf16 v[6:9], v[154:157], v[192:195], v[6:9]
	v_mfma_f32_16x16x32_bf16 v[66:69], v[146:149], v[200:203], v[66:69]
	v_mfma_f32_16x16x32_bf16 v[2:5], v[154:157], v[200:203], v[2:5]
	v_mfma_f32_16x16x32_bf16 v[58:61], v[146:149], v[208:211], v[58:61]
	v_mfma_f32_16x16x32_bf16 v[30:33], v[154:157], v[208:211], v[30:33]
	v_mfma_f32_16x16x32_bf16 v[78:81], v[150:153], v[188:191], v[78:81]
	v_mfma_f32_16x16x32_bf16 v[14:17], v[158:161], v[188:191], v[14:17]
	v_mfma_f32_16x16x32_bf16 v[70:73], v[150:153], v[196:199], v[70:73]
	v_mfma_f32_16x16x32_bf16 v[6:9], v[158:161], v[196:199], v[6:9]
	v_mfma_f32_16x16x32_bf16 v[66:69], v[150:153], v[204:207], v[66:69]
	v_mfma_f32_16x16x32_bf16 v[2:5], v[158:161], v[204:207], v[2:5]
	v_mfma_f32_16x16x32_bf16 v[58:61], v[150:153], v[212:215], v[58:61]
	v_mfma_f32_16x16x32_bf16 v[30:33], v[158:161], v[212:215], v[30:33]
	s_barrier
; #define PG8_STAGE(bufoff, gbase, voff) do { _Pragma("unroll") for (int _i = 0; _i < 2; ++_i) \
;         __builtin_amdgcn_global_load_lds((const unsigned*)((const char*)(gbase) + (voff)[_i]), (LAS unsigned*)(lds + (bufoff) + ldsw + _i * 8192), 16, 0, 0); } while (0)
; #define PG8_LDA(dst, b, h) do { _Pragma("unroll") for (int m = 0; m < 4; ++m) _Pragma("unroll") for (int k = 0; k < 2; ++k) dst[m][k] = *(const LAS bf16x8*)(lds + PG8_SA(b, h) + aoff + m * 2048 + k * 1024); } while (0)
; #define PG8_LDB(dst, b, h) do { _Pragma("unroll") for (int n = 0; n < 2; ++n) _Pragma("unroll") for (int k = 0; k < 2; ++k) dst[n][k] = *(const LAS bf16x8*)(lds + PG8_SB(b, h) + boff + n * 2048 + k * 1024); } while (0)
; #define PG8_MMA(ai, bj, At, Bt) do { __builtin_amdgcn_s_setprio(1); _Pragma("unroll") for (int m = 0; m < 4; ++m) _Pragma("unroll") for (int n = 0; n < 2; ++n) _Pragma("unroll") for (int k = 0; k < 2; ++k) \
;         acc[ai][bj][m][n] = __builtin_amdgcn_mfma_f32_16x16x32_bf16(Bt[n][k], At[m][k], acc[ai][bj][m][n], 0, 0, 0); __builtin_amdgcn_s_setprio(0); } while (0)
; #define PG8_WAIT_V(n) asm volatile("s_waitcnt vmcnt(" #n ")" ::: "memory")
; #define PG8_WAIT_L(n) asm volatile("s_waitcnt lgkmcnt(" #n ")" ::: "memory")
; #define PG8_BAR __builtin_amdgcn_s_barrier()
; #define PG8_SCHED __builtin_amdgcn_sched_barrier(0)
; template <class Epi, class Sched, int NSEG, int KK, int LDA, int LDB>
; __device__ __forceinline__ void gemm_phase(LAS unsigned char* lds, const Gemm g, const Sched& S, const Epi& E) {
;     ...
;             PG8_LDB(B0, 1, 0); PG8_LDB(B1, 1, 1); PG8_SCHED; PG8_LDA(At, 1, 0); PG8_STAGE(PG8_SA(0, 1), a2 + hstepA, voffA);
;             PG8_WAIT_V(8); PG8_WAIT_L(0); PG8_BAR; PG8_MMA(0, 0, At, B0); PG8_MMA(0, 1, At, B1); PG8_BAR; PG8_SCHED;
	s_setprio 0
	s_add_i32 s55, 0, 0x18000
	v_add_u32_e32 v0, s55, v252
	s_add_i32 s60, 0, 0x1c000
	ds_read_b128 v[118:121], v0
	ds_read_b128 v[134:137], v0 offset:1024
	ds_read_b128 v[138:141], v0 offset:2048
	ds_read_b128 v[142:145], v0 offset:3072
	v_add_u32_e32 v0, s60, v252
	ds_read_b128 v[146:149], v0
	ds_read_b128 v[150:153], v0 offset:1024
	ds_read_b128 v[154:157], v0 offset:2048
	ds_read_b128 v[158:161], v0 offset:3072
	s_add_u32 s44, s44, 0x40000
	s_addc_u32 s45, s45, 0
	s_mov_b32 m0, s77
	v_lshl_add_u64 v[222:223], s[44:45], 0, v[182:183]
	ds_read_b128 v[162:165], v166 offset:32768
	ds_read_b128 v[188:191], v166 offset:33792
	ds_read_b128 v[192:195], v166 offset:34816
	ds_read_b128 v[196:199], v166 offset:35840
	ds_read_b128 v[200:203], v166 offset:36864
	ds_read_b128 v[204:207], v166 offset:37888
	ds_read_b128 v[208:211], v166 offset:38912
	ds_read_b128 v[212:215], v166 offset:39936
	global_load_lds_dwordx4 v[222:223], off
	v_lshl_add_u64 v[222:223], s[44:45], 0, v[178:179]
	s_mov_b32 m0, s33
	s_nop 0
	global_load_lds_dwordx4 v[222:223], off
	s_waitcnt vmcnt(8)
	s_waitcnt lgkmcnt(0)
	s_barrier
	s_setprio 1
	v_mfma_f32_16x16x32_bf16 v[130:133], v[118:121], v[162:165], v[130:133]
	v_mfma_f32_16x16x32_bf16 v[126:129], v[138:141], v[162:165], v[126:129]
	v_mfma_f32_16x16x32_bf16 v[110:113], v[118:121], v[192:195], v[110:113]
	v_mfma_f32_16x16x32_bf16 v[46:49], v[138:141], v[192:195], v[46:49]
	v_mfma_f32_16x16x32_bf16 v[106:109], v[118:121], v[200:203], v[106:109]
	v_mfma_f32_16x16x32_bf16 v[42:45], v[138:141], v[200:203], v[42:45]
	v_mfma_f32_16x16x32_bf16 v[114:117], v[118:121], v[208:211], v[114:117]
	v_mfma_f32_16x16x32_bf16 v[50:53], v[138:141], v[208:211], v[50:53]
	v_mfma_f32_16x16x32_bf16 v[130:133], v[134:137], v[188:191], v[130:133]
	v_mfma_f32_16x16x32_bf16 v[126:129], v[142:145], v[188:191], v[126:129]
	v_mfma_f32_16x16x32_bf16 v[110:113], v[134:137], v[196:199], v[110:113]
	v_mfma_f32_16x16x32_bf16 v[46:49], v[142:145], v[196:199], v[46:49]
	v_mfma_f32_16x16x32_bf16 v[106:109], v[134:137], v[204:207], v[106:109]
	v_mfma_f32_16x16x32_bf16 v[42:45], v[142:145], v[204:207], v[42:45]
	v_mfma_f32_16x16x32_bf16 v[114:117], v[134:137], v[212:215], v[114:117]
	v_mfma_f32_16x16x32_bf16 v[50:53], v[142:145], v[212:215], v[50:53]
	s_setprio 0
	s_setprio 1
	v_mfma_f32_16x16x32_bf16 v[122:125], v[146:149], v[162:165], v[122:125]
	v_mfma_f32_16x16x32_bf16 v[62:65], v[154:157], v[162:165], v[62:65]
	v_mfma_f32_16x16x32_bf16 v[102:105], v[146:149], v[192:195], v[102:105]
	v_mfma_f32_16x16x32_bf16 v[38:41], v[154:157], v[192:195], v[38:41]
	v_mfma_f32_16x16x32_bf16 v[98:101], v[146:149], v[200:203], v[98:101]
	v_mfma_f32_16x16x32_bf16 v[34:37], v[154:157], v[200:203], v[34:37]
	v_mfma_f32_16x16x32_bf16 v[90:93], v[146:149], v[208:211], v[90:93]
	v_mfma_f32_16x16x32_bf16 v[54:57], v[154:157], v[208:211], v[54:57]
	v_mfma_f32_16x16x32_bf16 v[122:125], v[150:153], v[188:191], v[122:125]
	v_mfma_f32_16x16x32_bf16 v[62:65], v[158:161], v[188:191], v[62:65]
	v_mfma_f32_16x16x32_bf16 v[102:105], v[150:153], v[196:199], v[102:105]
	v_mfma_f32_16x16x32_bf16 v[38:41], v[158:161], v[196:199], v[38:41]
	v_mfma_f32_16x16x32_bf16 v[98:101], v[150:153], v[204:207], v[98:101]
	v_mfma_f32_16x16x32_bf16 v[34:37], v[158:161], v[204:207], v[34:37]
	v_mfma_f32_16x16x32_bf16 v[90:93], v[150:153], v[212:215], v[90:93]
	v_mfma_f32_16x16x32_bf16 v[54:57], v[158:161], v[212:215], v[54:57]
	s_barrier
; #define PG8_STAGE(bufoff, gbase, voff) do { _Pragma("unroll") for (int _i = 0; _i < 2; ++_i) \
;         __builtin_amdgcn_global_load_lds((const unsigned*)((const char*)(gbase) + (voff)[_i]), (LAS unsigned*)(lds + (bufoff) + ldsw + _i * 8192), 16, 0, 0); } while (0)
; #define PG8_LDA(dst, b, h) do { _Pragma("unroll") for (int m = 0; m < 4; ++m) _Pragma("unroll") for (int k = 0; k < 2; ++k) dst[m][k] = *(const LAS bf16x8*)(lds + PG8_SA(b, h) + aoff + m * 2048 + k * 1024); } while (0)
; #define PG8_MMA(ai, bj, At, Bt) do { __builtin_amdgcn_s_setprio(1); _Pragma("unroll") for (int m = 0; m < 4; ++m) _Pragma("unroll") for (int n = 0; n < 2; ++n) _Pragma("unroll") for (int k = 0; k < 2; ++k) \
;         acc[ai][bj][m][n] = __builtin_amdgcn_mfma_f32_16x16x32_bf16(Bt[n][k], At[m][k], acc[ai][bj][m][n], 0, 0, 0); __builtin_amdgcn_s_setprio(0); } while (0)
; #define PG8_WAIT_V(n) asm volatile("s_waitcnt vmcnt(" #n ")" ::: "memory")
; #define PG8_WAIT_L(n) asm volatile("s_waitcnt lgkmcnt(" #n ")" ::: "memory")
; #define PG8_BAR __builtin_amdgcn_s_barrier()
; #define PG8_SCHED __builtin_amdgcn_sched_barrier(0)
; template <class Epi, class Sched, int NSEG, int KK, int LDA, int LDB>
; __device__ __forceinline__ void gemm_phase(LAS unsigned char* lds, const Gemm g, const Sched& S, const Epi& E) {
;     ...
;             PG8_LDA(At, 1, 1); PG8_STAGE(PG8_SB(1, 0), b3, voffB); PG8_STAGE(PG8_SB(1, 1), b3 + hstepB, voffB); PG8_STAGE(PG8_SA(1, 0), a3, voffA);
;             PG8_WAIT_V(8); PG8_WAIT_L(0); PG8_BAR; PG8_MMA(1, 0, At, B0); PG8_MMA(1, 1, At, B1); PG8_BAR; PG8_SCHED;
;         }
;         if (wr == 0) PG8_BAR;
	s_setprio 0
	s_add_i32 s44, s55, s38
	v_lshl_add_u64 v[172:173], v[172:173], 0, s[28:29]
	s_mov_b32 m0, s44
	ds_read_b128 v[162:165], v166 offset:49152
	ds_read_b128 v[188:191], v166 offset:50176
	ds_read_b128 v[192:195], v166 offset:51200
	ds_read_b128 v[196:199], v166 offset:52224
	ds_read_b128 v[200:203], v166 offset:53248
	ds_read_b128 v[204:207], v166 offset:54272
	ds_read_b128 v[208:211], v166 offset:55296
	ds_read_b128 v[212:215], v166 offset:56320
	global_load_lds_dwordx4 v[172:173], off
	s_add_i32 m0, s44, 0x2000
	s_add_u32 s10, s10, 0x40080
	v_lshl_add_u64 v[172:173], v[216:217], 0, s[28:29]
	s_addc_u32 s11, s11, 0
	s_add_i32 s44, s60, s38
	global_load_lds_dwordx4 v[172:173], off
	v_lshl_add_u64 v[172:173], s[10:11], 0, v[180:181]
	s_mov_b32 m0, s44
	s_nop 0
	global_load_lds_dwordx4 v[172:173], off
	v_lshl_add_u64 v[172:173], s[10:11], 0, v[176:177]
	s_add_i32 m0, s44, 0x2000
	s_nop 0
	global_load_lds_dwordx4 v[172:173], off
	v_lshl_add_u64 v[172:173], v[218:219], 0, s[28:29]
	s_mov_b32 m0, s91
	s_nop 0
	global_load_lds_dwordx4 v[172:173], off
	v_lshl_add_u64 v[172:173], v[220:221], 0, s[28:29]
	s_mov_b32 m0, s94
	s_nop 0
	global_load_lds_dwordx4 v[172:173], off
	s_waitcnt vmcnt(8)
	s_waitcnt lgkmcnt(0)
	s_barrier
	s_setprio 1
	v_mfma_f32_16x16x32_bf16 v[94:97], v[118:121], v[162:165], v[94:97]
	v_mfma_f32_16x16x32_bf16 v[22:25], v[138:141], v[162:165], v[22:25]
	v_mfma_f32_16x16x32_bf16 v[86:89], v[118:121], v[192:195], v[86:89]
	v_mfma_f32_16x16x32_bf16 v[18:21], v[138:141], v[192:195], v[18:21]
	v_mfma_f32_16x16x32_bf16 v[74:77], v[118:121], v[200:203], v[74:77]
	v_mfma_f32_16x16x32_bf16 v[10:13], v[138:141], v[200:203], v[10:13]
	v_mfma_f32_16x16x32_bf16 v[82:85], v[118:121], v[208:211], v[82:85]
	v_mfma_f32_16x16x32_bf16 v[26:29], v[138:141], v[208:211], v[26:29]
	v_mfma_f32_16x16x32_bf16 v[94:97], v[134:137], v[188:191], v[94:97]
	v_mfma_f32_16x16x32_bf16 v[22:25], v[142:145], v[188:191], v[22:25]
	v_mfma_f32_16x16x32_bf16 v[86:89], v[134:137], v[196:199], v[86:89]
	v_mfma_f32_16x16x32_bf16 v[18:21], v[142:145], v[196:199], v[18:21]
	v_mfma_f32_16x16x32_bf16 v[74:77], v[134:137], v[204:207], v[74:77]
	v_mfma_f32_16x16x32_bf16 v[10:13], v[142:145], v[204:207], v[10:13]
	v_mfma_f32_16x16x32_bf16 v[82:85], v[134:137], v[212:215], v[82:85]
	v_mfma_f32_16x16x32_bf16 v[26:29], v[142:145], v[212:215], v[26:29]
	s_setprio 0
	s_setprio 1
	v_mfma_f32_16x16x32_bf16 v[78:81], v[146:149], v[162:165], v[78:81]
	v_mfma_f32_16x16x32_bf16 v[14:17], v[154:157], v[162:165], v[14:17]
	v_mfma_f32_16x16x32_bf16 v[70:73], v[146:149], v[192:195], v[70:73]
	v_mfma_f32_16x16x32_bf16 v[6:9], v[154:157], v[192:195], v[6:9]
	v_mfma_f32_16x16x32_bf16 v[66:69], v[146:149], v[200:203], v[66:69]
	v_mfma_f32_16x16x32_bf16 v[2:5], v[154:157], v[200:203], v[2:5]
	v_mfma_f32_16x16x32_bf16 v[58:61], v[146:149], v[208:211], v[58:61]
	v_mfma_f32_16x16x32_bf16 v[30:33], v[154:157], v[208:211], v[30:33]
	v_mfma_f32_16x16x32_bf16 v[78:81], v[150:153], v[188:191], v[78:81]
	v_mfma_f32_16x16x32_bf16 v[14:17], v[158:161], v[188:191], v[14:17]
	v_mfma_f32_16x16x32_bf16 v[70:73], v[150:153], v[196:199], v[70:73]
	v_mfma_f32_16x16x32_bf16 v[6:9], v[158:161], v[196:199], v[6:9]
	v_mfma_f32_16x16x32_bf16 v[66:69], v[150:153], v[204:207], v[66:69]
	v_mfma_f32_16x16x32_bf16 v[2:5], v[158:161], v[204:207], v[2:5]
	v_mfma_f32_16x16x32_bf16 v[58:61], v[150:153], v[212:215], v[58:61]
	v_mfma_f32_16x16x32_bf16 v[30:33], v[158:161], v[212:215], v[30:33]
	s_barrier
	s_setprio 0
	s_add_i32 s53, s53, 2
	s_add_u32 s42, s42, 0x100
	s_addc_u32 s43, s43, 0
	s_add_u32 s50, s50, 0x100
	s_addc_u32 s51, s51, 0
	s_cmp_gt_u32 s53, 13
	s_cbranch_scc0 .LBB0_1065
	s_mov_b32 s101, 1
	s_and_b64 vcc, exec, s[24:25]
	s_cbranch_vccz .LBB0_1068
	s_barrier

; #define PG8_STAGE(bufoff, gbase, voff) do { _Pragma("unroll") for (int _i = 0; _i < 2; ++_i) \
;         __builtin_amdgcn_global_load_lds((const unsigned*)((const char*)(gbase) + (voff)[_i]), (LAS unsigned*)(lds + (bufoff) + ldsw + _i * 8192), 16, 0, 0); } while (0)
; #define PG8_LDA(dst, b, h) do { _Pragma("unroll") for (int m = 0; m < 4; ++m) _Pragma("unroll") for (int k = 0; k < 2; ++k) dst[m][k] = *(const LAS bf16x8*)(lds + PG8_SA(b, h) + aoff + m * 2048 + k * 1024); } while (0)
; #define PG8_MMA(ai, bj, At, Bt) do { __builtin_amdgcn_s_setprio(1); _Pragma("unroll") for (int m = 0; m < 4; ++m) _Pragma("unroll") for (int n = 0; n < 2; ++n) _Pragma("unroll") for (int k = 0; k < 2; ++k) \
;         acc[ai][bj][m][n] = __builtin_amdgcn_mfma_f32_16x16x32_bf16(Bt[n][k], At[m][k], acc[ai][bj][m][n], 0, 0, 0); __builtin_amdgcn_s_setprio(0); } while (0)
; #define PG8_WAIT_V(n) asm volatile("s_waitcnt vmcnt(" #n ")" ::: "memory")
; #define PG8_WAIT_L(n) asm volatile("s_waitcnt lgkmcnt(" #n ")" ::: "memory")
; #define PG8_BAR __builtin_amdgcn_s_barrier()
; #define PG8_SCHED __builtin_amdgcn_sched_barrier(0)
; template <class Epi, class Sched, int NSEG, int KK, int LDA, int LDB>
; __device__ __forceinline__ void gemm_phase(LAS unsigned char* lds, const Gemm g, const Sched& S, const Epi& E) {
;     ...
;             PG8_WAIT_V(8); PG8_WAIT_L(0); PG8_BAR; PG8_MMA(0, 0, At, B0); PG8_MMA(0, 1, At, B1); PG8_BAR; PG8_SCHED;
;             PG8_LDA(At, 0, 1); PG8_STAGE(PG8_SB(0, 0), b2, voffB); PG8_STAGE(PG8_SB(0, 1), b2 + hstepB, voffB); PG8_STAGE(PG8_SA(0, 0), a2, voffA);
;             PG8_WAIT_V(8); PG8_WAIT_L(0); PG8_BAR; PG8_MMA(1, 0, At, B0); PG8_MMA(1, 1, At, B1); PG8_BAR; PG8_SCHED;
.Lskw_5_1:
	s_waitcnt lgkmcnt(0)
	s_barrier
	s_setprio 1
	v_mfma_f32_16x16x32_bf16 v[126:129], v[136:139], v[180:183], v[126:129]
	v_mfma_f32_16x16x32_bf16 v[122:125], v[144:147], v[180:183], v[122:125]
	v_mfma_f32_16x16x32_bf16 v[110:113], v[136:139], v[188:191], v[110:113]
	v_mfma_f32_16x16x32_bf16 v[106:109], v[144:147], v[188:191], v[106:109]
	v_mfma_f32_16x16x32_bf16 v[94:97], v[136:139], v[196:199], v[94:97]
	v_mfma_f32_16x16x32_bf16 v[90:93], v[144:147], v[196:199], v[90:93]
	v_mfma_f32_16x16x32_bf16 v[78:81], v[136:139], v[204:207], v[78:81]
	v_mfma_f32_16x16x32_bf16 v[74:77], v[144:147], v[204:207], v[74:77]
	v_mfma_f32_16x16x32_bf16 v[126:129], v[140:143], v[184:187], v[126:129]
	v_mfma_f32_16x16x32_bf16 v[122:125], v[148:151], v[184:187], v[122:125]
	v_mfma_f32_16x16x32_bf16 v[110:113], v[140:143], v[192:195], v[110:113]
	v_mfma_f32_16x16x32_bf16 v[106:109], v[148:151], v[192:195], v[106:109]
	v_mfma_f32_16x16x32_bf16 v[94:97], v[140:143], v[200:203], v[94:97]
	v_mfma_f32_16x16x32_bf16 v[90:93], v[148:151], v[200:203], v[90:93]
	v_mfma_f32_16x16x32_bf16 v[78:81], v[140:143], v[208:211], v[78:81]
	v_mfma_f32_16x16x32_bf16 v[74:77], v[148:151], v[208:211], v[74:77]
	s_setprio 0
	s_setprio 1
	v_mfma_f32_16x16x32_bf16 v[118:121], v[152:155], v[180:183], v[118:121]
	v_mfma_f32_16x16x32_bf16 v[114:117], v[160:163], v[180:183], v[114:117]
	v_mfma_f32_16x16x32_bf16 v[102:105], v[152:155], v[188:191], v[102:105]
	v_mfma_f32_16x16x32_bf16 v[98:101], v[160:163], v[188:191], v[98:101]
	v_mfma_f32_16x16x32_bf16 v[86:89], v[152:155], v[196:199], v[86:89]
	v_mfma_f32_16x16x32_bf16 v[82:85], v[160:163], v[196:199], v[82:85]
	v_mfma_f32_16x16x32_bf16 v[70:73], v[152:155], v[204:207], v[70:73]
	v_mfma_f32_16x16x32_bf16 v[66:69], v[160:163], v[204:207], v[66:69]
	v_mfma_f32_16x16x32_bf16 v[118:121], v[156:159], v[184:187], v[118:121]
	v_mfma_f32_16x16x32_bf16 v[114:117], v[176:179], v[184:187], v[114:117]
	v_mfma_f32_16x16x32_bf16 v[102:105], v[156:159], v[192:195], v[102:105]
	v_mfma_f32_16x16x32_bf16 v[98:101], v[176:179], v[192:195], v[98:101]
	v_mfma_f32_16x16x32_bf16 v[86:89], v[156:159], v[200:203], v[86:89]
	v_mfma_f32_16x16x32_bf16 v[82:85], v[176:179], v[200:203], v[82:85]
	v_mfma_f32_16x16x32_bf16 v[70:73], v[156:159], v[208:211], v[70:73]
	v_mfma_f32_16x16x32_bf16 v[66:69], v[176:179], v[208:211], v[66:69]
	s_barrier
	s_setprio 0
	s_add_i32 s42, s61, s13
	v_lshl_add_u64 v[166:167], s[10:11], 0, v[0:1]
	s_mov_b32 m0, s42
	ds_read_b128 v[180:183], v165 offset:16384
	ds_read_b128 v[184:187], v165 offset:17408
	ds_read_b128 v[188:191], v165 offset:18432
	ds_read_b128 v[192:195], v165 offset:19456
	ds_read_b128 v[196:199], v165 offset:20480
	ds_read_b128 v[200:203], v165 offset:21504
	ds_read_b128 v[204:207], v165 offset:22528
	ds_read_b128 v[208:211], v165 offset:23552
	global_load_lds_dwordx4 v[166:167], off
	s_add_i32 m0, s42, 0x2000
	s_add_u32 s42, s10, 0xb0000
	v_lshl_add_u64 v[172:173], s[10:11], 0, v[130:131]
	s_addc_u32 s43, s11, 0
	s_add_i32 s61, s62, s13
	global_load_lds_dwordx4 v[172:173], off
	v_lshl_add_u64 v[212:213], s[42:43], 0, v[0:1]
	s_mov_b32 m0, s61
	v_lshl_add_u64 v[214:215], s[46:47], 0, v[130:131]
	global_load_lds_dwordx4 v[212:213], off
	v_lshl_add_u64 v[212:213], s[42:43], 0, v[130:131]
	s_add_i32 m0, s61, 0x2000
	s_nop 0
	global_load_lds_dwordx4 v[212:213], off
	v_lshl_add_u64 v[212:213], s[46:47], 0, v[0:1]
	s_mov_b32 m0, s48
	s_nop 0
	global_load_lds_dwordx4 v[212:213], off
	s_mov_b32 m0, s49
	s_nop 0
	global_load_lds_dwordx4 v[214:215], off
	s_cmp_lg_u32 s101, 0
	s_cbranch_scc1 .Lskw_5_2
	s_waitcnt vmcnt(8)
.Lskw_5_2:
	s_mov_b32 s101, 0
	s_waitcnt lgkmcnt(0)
	s_barrier
	s_setprio 1
	v_mfma_f32_16x16x32_bf16 v[62:65], v[136:139], v[180:183], v[62:65]
	v_mfma_f32_16x16x32_bf16 v[58:61], v[144:147], v[180:183], v[58:61]
	v_mfma_f32_16x16x32_bf16 v[46:49], v[136:139], v[188:191], v[46:49]
	v_mfma_f32_16x16x32_bf16 v[42:45], v[144:147], v[188:191], v[42:45]
	v_mfma_f32_16x16x32_bf16 v[30:33], v[136:139], v[196:199], v[30:33]
	v_mfma_f32_16x16x32_bf16 v[26:29], v[144:147], v[196:199], v[26:29]
	v_mfma_f32_16x16x32_bf16 v[14:17], v[136:139], v[204:207], v[14:17]
	v_mfma_f32_16x16x32_bf16 v[10:13], v[144:147], v[204:207], v[10:13]
	v_mfma_f32_16x16x32_bf16 v[62:65], v[140:143], v[184:187], v[62:65]
	v_mfma_f32_16x16x32_bf16 v[58:61], v[148:151], v[184:187], v[58:61]
	v_mfma_f32_16x16x32_bf16 v[46:49], v[140:143], v[192:195], v[46:49]
	v_mfma_f32_16x16x32_bf16 v[42:45], v[148:151], v[192:195], v[42:45]
	v_mfma_f32_16x16x32_bf16 v[30:33], v[140:143], v[200:203], v[30:33]
	v_mfma_f32_16x16x32_bf16 v[26:29], v[148:151], v[200:203], v[26:29]
	v_mfma_f32_16x16x32_bf16 v[14:17], v[140:143], v[208:211], v[14:17]
	v_mfma_f32_16x16x32_bf16 v[10:13], v[148:151], v[208:211], v[10:13]
	s_setprio 0
	s_setprio 1
	v_mfma_f32_16x16x32_bf16 v[54:57], v[152:155], v[180:183], v[54:57]
	v_mfma_f32_16x16x32_bf16 v[50:53], v[160:163], v[180:183], v[50:53]
	v_mfma_f32_16x16x32_bf16 v[38:41], v[152:155], v[188:191], v[38:41]
	v_mfma_f32_16x16x32_bf16 v[34:37], v[160:163], v[188:191], v[34:37]
	v_mfma_f32_16x16x32_bf16 v[22:25], v[152:155], v[196:199], v[22:25]
	v_mfma_f32_16x16x32_bf16 v[18:21], v[160:163], v[196:199], v[18:21]
	v_mfma_f32_16x16x32_bf16 v[6:9], v[152:155], v[204:207], v[6:9]
	v_mfma_f32_16x16x32_bf16 v[2:5], v[160:163], v[204:207], v[2:5]
	v_mfma_f32_16x16x32_bf16 v[54:57], v[156:159], v[184:187], v[54:57]
	v_mfma_f32_16x16x32_bf16 v[50:53], v[176:179], v[184:187], v[50:53]
	v_mfma_f32_16x16x32_bf16 v[38:41], v[156:159], v[192:195], v[38:41]
	v_mfma_f32_16x16x32_bf16 v[34:37], v[176:179], v[192:195], v[34:37]
	v_mfma_f32_16x16x32_bf16 v[22:25], v[156:159], v[200:203], v[22:25]
	v_mfma_f32_16x16x32_bf16 v[18:21], v[176:179], v[200:203], v[18:21]
	v_mfma_f32_16x16x32_bf16 v[6:9], v[156:159], v[208:211], v[6:9]
	v_mfma_f32_16x16x32_bf16 v[2:5], v[176:179], v[208:211], v[2:5]
	s_barrier
; #define PG8_STAGE(bufoff, gbase, voff) do { _Pragma("unroll") for (int _i = 0; _i < 2; ++_i) \
;         __builtin_amdgcn_global_load_lds((const unsigned*)((const char*)(gbase) + (voff)[_i]), (LAS unsigned*)(lds + (bufoff) + ldsw + _i * 8192), 16, 0, 0); } while (0)
; #define PG8_LDA(dst, b, h) do { _Pragma("unroll") for (int m = 0; m < 4; ++m) _Pragma("unroll") for (int k = 0; k < 2; ++k) dst[m][k] = *(const LAS bf16x8*)(lds + PG8_SA(b, h) + aoff + m * 2048 + k * 1024); } while (0)
; #define PG8_LDB(dst, b, h) do { _Pragma("unroll") for (int n = 0; n < 2; ++n) _Pragma("unroll") for (int k = 0; k < 2; ++k) dst[n][k] = *(const LAS bf16x8*)(lds + PG8_SB(b, h) + boff + n * 2048 + k * 1024); } while (0)
; #define PG8_MMA(ai, bj, At, Bt) do { __builtin_amdgcn_s_setprio(1); _Pragma("unroll") for (int m = 0; m < 4; ++m) _Pragma("unroll") for (int n = 0; n < 2; ++n) _Pragma("unroll") for (int k = 0; k < 2; ++k) \
;         acc[ai][bj][m][n] = __builtin_amdgcn_mfma_f32_16x16x32_bf16(Bt[n][k], At[m][k], acc[ai][bj][m][n], 0, 0, 0); __builtin_amdgcn_s_setprio(0); } while (0)
; #define PG8_WAIT_V(n) asm volatile("s_waitcnt vmcnt(" #n ")" ::: "memory")
; #define PG8_WAIT_L(n) asm volatile("s_waitcnt lgkmcnt(" #n ")" ::: "memory")
; #define PG8_BAR __builtin_amdgcn_s_barrier()
; #define PG8_SCHED __builtin_amdgcn_sched_barrier(0)
; template <class Epi, class Sched, int NSEG, int KK, int LDA, int LDB>
; __device__ __forceinline__ void gemm_phase(LAS unsigned char* lds, const Gemm g, const Sched& S, const Epi& E) {
;     ...
;             PG8_LDB(B0, 1, 0); PG8_LDB(B1, 1, 1); PG8_SCHED; PG8_LDA(At, 1, 0); PG8_STAGE(PG8_SA(0, 1), a2 + hstepA, voffA);
;             PG8_WAIT_V(8); PG8_WAIT_L(0); PG8_BAR; PG8_MMA(0, 0, At, B0); PG8_MMA(0, 1, At, B1); PG8_BAR; PG8_SCHED;
	s_setprio 0
	s_add_i32 s61, 0, 0x18000
	s_add_i32 s62, 0, 0x1c000
	v_add_u32_e32 v148, s61, v164
	v_add_u32_e32 v176, s62, v164
	ds_read_b128 v[136:139], v148
	ds_read_b128 v[140:143], v148 offset:1024
	ds_read_b128 v[144:147], v148 offset:256
	ds_read_b128 v[148:151], v148 offset:1280
	ds_read_b128 v[152:155], v176
	ds_read_b128 v[156:159], v176 offset:1024
	ds_read_b128 v[160:163], v176 offset:256
	ds_read_b128 v[176:179], v176 offset:1280
	s_add_u32 s42, s46, 0xb0000
	s_addc_u32 s43, s47, 0
	s_mov_b32 m0, s50
	v_lshl_add_u64 v[216:217], s[42:43], 0, v[0:1]
	ds_read_b128 v[180:183], v165 offset:32768
	ds_read_b128 v[184:187], v165 offset:33792
	ds_read_b128 v[188:191], v165 offset:34816
	ds_read_b128 v[192:195], v165 offset:35840
	ds_read_b128 v[196:199], v165 offset:36864
	ds_read_b128 v[200:203], v165 offset:37888
	ds_read_b128 v[204:207], v165 offset:38912
	ds_read_b128 v[208:211], v165 offset:39936
	global_load_lds_dwordx4 v[216:217], off
	v_lshl_add_u64 v[216:217], s[42:43], 0, v[130:131]
	s_mov_b32 m0, s51
	s_nop 0
	global_load_lds_dwordx4 v[216:217], off
	s_waitcnt vmcnt(8)
	s_waitcnt lgkmcnt(0)
	s_barrier
	s_setprio 1
	v_mfma_f32_16x16x32_bf16 v[126:129], v[136:139], v[180:183], v[126:129]
	v_mfma_f32_16x16x32_bf16 v[122:125], v[144:147], v[180:183], v[122:125]
	v_mfma_f32_16x16x32_bf16 v[110:113], v[136:139], v[188:191], v[110:113]
	v_mfma_f32_16x16x32_bf16 v[106:109], v[144:147], v[188:191], v[106:109]
	v_mfma_f32_16x16x32_bf16 v[94:97], v[136:139], v[196:199], v[94:97]
	v_mfma_f32_16x16x32_bf16 v[90:93], v[144:147], v[196:199], v[90:93]
	v_mfma_f32_16x16x32_bf16 v[78:81], v[136:139], v[204:207], v[78:81]
	v_mfma_f32_16x16x32_bf16 v[74:77], v[144:147], v[204:207], v[74:77]
	v_mfma_f32_16x16x32_bf16 v[126:129], v[140:143], v[184:187], v[126:129]
	v_mfma_f32_16x16x32_bf16 v[122:125], v[148:151], v[184:187], v[122:125]
	v_mfma_f32_16x16x32_bf16 v[110:113], v[140:143], v[192:195], v[110:113]
	v_mfma_f32_16x16x32_bf16 v[106:109], v[148:151], v[192:195], v[106:109]
	v_mfma_f32_16x16x32_bf16 v[94:97], v[140:143], v[200:203], v[94:97]
	v_mfma_f32_16x16x32_bf16 v[90:93], v[148:151], v[200:203], v[90:93]
	v_mfma_f32_16x16x32_bf16 v[78:81], v[140:143], v[208:211], v[78:81]
	v_mfma_f32_16x16x32_bf16 v[74:77], v[148:151], v[208:211], v[74:77]
	s_setprio 0
	s_setprio 1
	v_mfma_f32_16x16x32_bf16 v[118:121], v[152:155], v[180:183], v[118:121]
	v_mfma_f32_16x16x32_bf16 v[114:117], v[160:163], v[180:183], v[114:117]
	v_mfma_f32_16x16x32_bf16 v[102:105], v[152:155], v[188:191], v[102:105]
	v_mfma_f32_16x16x32_bf16 v[98:101], v[160:163], v[188:191], v[98:101]
	v_mfma_f32_16x16x32_bf16 v[86:89], v[152:155], v[196:199], v[86:89]
	v_mfma_f32_16x16x32_bf16 v[82:85], v[160:163], v[196:199], v[82:85]
	v_mfma_f32_16x16x32_bf16 v[70:73], v[152:155], v[204:207], v[70:73]
	v_mfma_f32_16x16x32_bf16 v[66:69], v[160:163], v[204:207], v[66:69]
	v_mfma_f32_16x16x32_bf16 v[118:121], v[156:159], v[184:187], v[118:121]
	v_mfma_f32_16x16x32_bf16 v[114:117], v[176:179], v[184:187], v[114:117]
	v_mfma_f32_16x16x32_bf16 v[102:105], v[156:159], v[192:195], v[102:105]
	v_mfma_f32_16x16x32_bf16 v[98:101], v[176:179], v[192:195], v[98:101]
	v_mfma_f32_16x16x32_bf16 v[86:89], v[156:159], v[200:203], v[86:89]
	v_mfma_f32_16x16x32_bf16 v[82:85], v[176:179], v[200:203], v[82:85]
	v_mfma_f32_16x16x32_bf16 v[70:73], v[156:159], v[208:211], v[70:73]
	v_mfma_f32_16x16x32_bf16 v[66:69], v[176:179], v[208:211], v[66:69]
	s_barrier
; #define PG8_STAGE(bufoff, gbase, voff) do { _Pragma("unroll") for (int _i = 0; _i < 2; ++_i) \
;         __builtin_amdgcn_global_load_lds((const unsigned*)((const char*)(gbase) + (voff)[_i]), (LAS unsigned*)(lds + (bufoff) + ldsw + _i * 8192), 16, 0, 0); } while (0)
; #define PG8_LDA(dst, b, h) do { _Pragma("unroll") for (int m = 0; m < 4; ++m) _Pragma("unroll") for (int k = 0; k < 2; ++k) dst[m][k] = *(const LAS bf16x8*)(lds + PG8_SA(b, h) + aoff + m * 2048 + k * 1024); } while (0)
; #define PG8_MMA(ai, bj, At, Bt) do { __builtin_amdgcn_s_setprio(1); _Pragma("unroll") for (int m = 0; m < 4; ++m) _Pragma("unroll") for (int n = 0; n < 2; ++n) _Pragma("unroll") for (int k = 0; k < 2; ++k) \
;         acc[ai][bj][m][n] = __builtin_amdgcn_mfma_f32_16x16x32_bf16(Bt[n][k], At[m][k], acc[ai][bj][m][n], 0, 0, 0); __builtin_amdgcn_s_setprio(0); } while (0)
; #define PG8_WAIT_V(n) asm volatile("s_waitcnt vmcnt(" #n ")" ::: "memory")
; #define PG8_WAIT_L(n) asm volatile("s_waitcnt lgkmcnt(" #n ")" ::: "memory")
; #define PG8_BAR __builtin_amdgcn_s_barrier()
; #define PG8_SCHED __builtin_amdgcn_sched_barrier(0)
; template <class Epi, class Sched, int NSEG, int KK, int LDA, int LDB>
; __device__ __forceinline__ void gemm_phase(LAS unsigned char* lds, const Gemm g, const Sched& S, const Epi& E) {
;     ...
;             PG8_LDA(At, 1, 1); PG8_STAGE(PG8_SB(1, 0), b3, voffB); PG8_STAGE(PG8_SB(1, 1), b3 + hstepB, voffB); PG8_STAGE(PG8_SA(1, 0), a3, voffA);
;             PG8_WAIT_V(8); PG8_WAIT_L(0); PG8_BAR; PG8_MMA(1, 0, At, B0); PG8_MMA(1, 1, At, B1); PG8_BAR; PG8_SCHED;
;         }
;         if (wr == 0) PG8_BAR;
	s_setprio 0
	s_add_i32 s42, s61, s13
	v_lshl_add_u64 v[166:167], v[166:167], 0, s[28:29]
	s_mov_b32 m0, s42
	ds_read_b128 v[180:183], v165 offset:49152
	ds_read_b128 v[184:187], v165 offset:50176
	ds_read_b128 v[188:191], v165 offset:51200
	ds_read_b128 v[192:195], v165 offset:52224
	ds_read_b128 v[196:199], v165 offset:53248
	ds_read_b128 v[200:203], v165 offset:54272
	ds_read_b128 v[204:207], v165 offset:55296
	ds_read_b128 v[208:211], v165 offset:56320
	global_load_lds_dwordx4 v[166:167], off
	s_add_i32 m0, s42, 0x2000
	s_add_u32 s10, s10, 0xb0080
	v_lshl_add_u64 v[166:167], v[172:173], 0, s[28:29]
	s_addc_u32 s11, s11, 0
	s_add_i32 s42, s62, s13
	global_load_lds_dwordx4 v[166:167], off
	v_lshl_add_u64 v[166:167], s[10:11], 0, v[0:1]
	s_mov_b32 m0, s42
	s_nop 0
	global_load_lds_dwordx4 v[166:167], off
	v_lshl_add_u64 v[166:167], s[10:11], 0, v[130:131]
	s_add_i32 m0, s42, 0x2000
	s_nop 0
	global_load_lds_dwordx4 v[166:167], off
	v_lshl_add_u64 v[166:167], v[212:213], 0, s[28:29]
	s_mov_b32 m0, s53
	s_nop 0
	global_load_lds_dwordx4 v[166:167], off
	v_lshl_add_u64 v[166:167], v[214:215], 0, s[28:29]
	s_mov_b32 m0, s54
	s_nop 0
	global_load_lds_dwordx4 v[166:167], off
	s_waitcnt vmcnt(8)
	s_waitcnt lgkmcnt(0)
	s_barrier
	s_setprio 1
	v_mfma_f32_16x16x32_bf16 v[62:65], v[136:139], v[180:183], v[62:65]
	v_mfma_f32_16x16x32_bf16 v[58:61], v[144:147], v[180:183], v[58:61]
	v_mfma_f32_16x16x32_bf16 v[46:49], v[136:139], v[188:191], v[46:49]
	v_mfma_f32_16x16x32_bf16 v[42:45], v[144:147], v[188:191], v[42:45]
	v_mfma_f32_16x16x32_bf16 v[30:33], v[136:139], v[196:199], v[30:33]
	v_mfma_f32_16x16x32_bf16 v[26:29], v[144:147], v[196:199], v[26:29]
	v_mfma_f32_16x16x32_bf16 v[14:17], v[136:139], v[204:207], v[14:17]
	v_mfma_f32_16x16x32_bf16 v[10:13], v[144:147], v[204:207], v[10:13]
	v_mfma_f32_16x16x32_bf16 v[62:65], v[140:143], v[184:187], v[62:65]
	v_mfma_f32_16x16x32_bf16 v[58:61], v[148:151], v[184:187], v[58:61]
	v_mfma_f32_16x16x32_bf16 v[46:49], v[140:143], v[192:195], v[46:49]
	v_mfma_f32_16x16x32_bf16 v[42:45], v[148:151], v[192:195], v[42:45]
	v_mfma_f32_16x16x32_bf16 v[30:33], v[140:143], v[200:203], v[30:33]
	v_mfma_f32_16x16x32_bf16 v[26:29], v[148:151], v[200:203], v[26:29]
	v_mfma_f32_16x16x32_bf16 v[14:17], v[140:143], v[208:211], v[14:17]
	v_mfma_f32_16x16x32_bf16 v[10:13], v[148:151], v[208:211], v[10:13]
	s_setprio 0
	s_setprio 1
	v_mfma_f32_16x16x32_bf16 v[54:57], v[152:155], v[180:183], v[54:57]
	v_mfma_f32_16x16x32_bf16 v[50:53], v[160:163], v[180:183], v[50:53]
	v_mfma_f32_16x16x32_bf16 v[38:41], v[152:155], v[188:191], v[38:41]
	v_mfma_f32_16x16x32_bf16 v[34:37], v[160:163], v[188:191], v[34:37]
	v_mfma_f32_16x16x32_bf16 v[22:25], v[152:155], v[196:199], v[22:25]
	v_mfma_f32_16x16x32_bf16 v[18:21], v[160:163], v[196:199], v[18:21]
	v_mfma_f32_16x16x32_bf16 v[6:9], v[152:155], v[204:207], v[6:9]
	v_mfma_f32_16x16x32_bf16 v[2:5], v[160:163], v[204:207], v[2:5]
	v_mfma_f32_16x16x32_bf16 v[54:57], v[156:159], v[184:187], v[54:57]
	v_mfma_f32_16x16x32_bf16 v[50:53], v[176:179], v[184:187], v[50:53]
	v_mfma_f32_16x16x32_bf16 v[38:41], v[156:159], v[192:195], v[38:41]
	v_mfma_f32_16x16x32_bf16 v[34:37], v[176:179], v[192:195], v[34:37]
	v_mfma_f32_16x16x32_bf16 v[22:25], v[156:159], v[200:203], v[22:25]
	v_mfma_f32_16x16x32_bf16 v[18:21], v[176:179], v[200:203], v[18:21]
	v_mfma_f32_16x16x32_bf16 v[6:9], v[156:159], v[208:211], v[6:9]
	v_mfma_f32_16x16x32_bf16 v[2:5], v[176:179], v[208:211], v[2:5]
	s_barrier
	s_setprio 0
	s_add_i32 s60, s60, 2
	s_add_u32 s58, s58, 0x100
	s_addc_u32 s59, s59, 0
	s_cmp_gt_u32 s60, 41
	s_mov_b64 s[42:43], s[40:41]
	s_cbranch_scc0 .LBB0_1258
	s_mov_b32 s101, 1
	s_and_b64 vcc, exec, s[8:9]
	s_cbranch_vccz .LBB0_1261
	s_barrier
